# v12 + GEMM K-loops: first iteration peeled with C=0 MFMAs, 128 accumulator-zeroing v_mov per tile removed; bit-identical
# speedup vs baseline: 1.0084x; 1.0084x over previous
; #define PG8_STAGE(bufoff, gbase, voff) do { _Pragma("unroll") for (int _i = 0; _i < 2; ++_i) \
;         __builtin_amdgcn_global_load_lds((const unsigned*)((const char*)(gbase) + (voff)[_i]), (PG8_LAS unsigned*)(lds + (bufoff) + ldsw + _i * 8192), 16, 0, 0); } while (0)
; #define PG8_LDA(dst, b, h) do { _Pragma("unroll") for (int m = 0; m < 4; ++m) _Pragma("unroll") for (int k = 0; k < 2; ++k) dst[m][k] = *(const PG8_LAS bf16x8*)(lds + PG8_SA(b, h) + aoff + m * 2048 + k * 1024); } while (0)
; template <class Epi, class Sched, bool ALIGN_EPI = false, bool SP2 = false>
; __device__ __forceinline__ void gemm_phase(PG8_LAS unsigned char* lds, const Gemm g, const Sched& S, const Epi& E) {
;     ...
;         const bool has_next = S.next(ui + 1, nxt);
;         const char* nA = has_next ? (const char*)g.A + (size_t)nxt.pm * tstepA : cA; const char* nB = has_next ? (const char*)g.Bt + (size_t)nxt.pn * tstep : cB;
;         for (int t = 0; t < nt; t += 2) {
;             const bool last = (t == nt - 2);
;             const char* a1 = cA + (size_t)(t + 1) * kstepA;
;             const char* a2 = last ? nA : cA + (size_t)(t + 2) * kstepA; const char* b2 = last ? nB : cB + (size_t)(t + 2) * kstep;
;             const char* a3 = a2 + kstepA; const char* b3 = b2 + kstep;
;             if (last && has_next) S.a_ready(nxt);
;             if constexpr (SP2) {
;             PG8_LDB(B0, 0, 0); PG8_LDB(B1, 0, 1); PG8_SCHED; PG8_LDA(At, 0, 0); PG8_STAGE(PG8_SA(1, 1), a1 + hstepA, voffA);
;             PG8_WAIT_V(8); PG8_WAIT_L(0); PG8_BAR; PG8_MMA(0, 0, At, B0); PG8_MMA(0, 1, At, B1); PG8_BAR; PG8_SCHED;
;             PG8_LDA(At, 0, 1); PG8_STAGE(PG8_SB(0, 0), b2, voffB); PG8_STAGE(PG8_SB(0, 1), b2 + hstep, voffB); PG8_STAGE(PG8_SA(0, 0), a2, voffA);
;             PG8_WAIT_V(8); PG8_WAIT_L(0); PG8_BAR; PG8_MMA(1, 0, At, B0); PG8_MMA(1, 1, At, B1); PG8_BAR; PG8_SCHED;
;             PG8_LDB(B0, 1, 0); PG8_LDB(B1, 1, 1); PG8_SCHED; PG8_LDA(At, 1, 0); PG8_STAGE(PG8_SA(0, 1), a2 + hstepA, voffA);
;             PG8_WAIT_V(8); PG8_WAIT_L(0); PG8_BAR; PG8_MMA(0, 0, At, B0); PG8_MMA(0, 1, At, B1); PG8_BAR; PG8_SCHED;
;             PG8_LDA(At, 1, 1); PG8_STAGE(PG8_SB(1, 0), b3, voffB); PG8_STAGE(PG8_SB(1, 1), b3 + hstep, voffB); PG8_STAGE(PG8_SA(1, 0), a3, voffA);
;             PG8_WAIT_V(8); PG8_WAIT_L(0); PG8_BAR; PG8_MMA(1, 0, At, B0); PG8_MMA(1, 1, At, B1); PG8_BAR; PG8_SCHED;
.LBB0_195:
	s_ashr_i32 s27, s26, 31
	s_lshl_b64 s[38:39], s[26:27], 19
	s_add_u32 s38, s20, s38
	s_addc_u32 s39, s21, s39
	s_and_b64 s[40:41], s[36:37], exec
	s_cselect_b32 s27, s39, s45
	s_cselect_b32 s54, s38, s44
	s_ashr_i32 s25, s24, 31
	s_lshl_b64 s[40:41], s[24:25], 19
	s_add_u32 s40, s2, s40
	s_addc_u32 s41, s3, s41
	s_and_b64 s[46:47], s[36:37], exec
	s_cselect_b32 s25, s41, s43
	s_cselect_b32 s55, s40, s42
	s_add_u32 s56, s42, 0x100
	s_addc_u32 s57, s43, 0
	s_add_u32 s42, s44, 0x40080
	s_addc_u32 s43, s45, 0
	s_mov_b32 s58, -2
	s_add_u32 s44, s42, 0xfffc0080
	s_addc_u32 s45, s43, -1
	s_add_i32 s59, 0, 0x10000
	s_cmp_eq_u32 s58, 12
	s_cselect_b32 s47, s27, s45
	s_cselect_b32 s46, s54, s44
	s_cselect_b32 s45, s25, s57
	s_cselect_b32 s44, s55, s56
	s_add_i32 s62, 0, 0x14000
	v_add_u32_e32 v154, s59, v143
	v_add_u32_e32 v166, s62, v143
	ds_read_b128 v[138:141], v154
	ds_read_b128 v[146:149], v154 offset:1024
	ds_read_b128 v[150:153], v154 offset:2048
	ds_read_b128 v[154:157], v154 offset:3072
	ds_read_b128 v[158:161], v166
	ds_read_b128 v[162:165], v166 offset:1024
	ds_read_b128 v[170:173], v166 offset:2048
	ds_read_b128 v[188:191], v166 offset:3072
	v_lshl_add_u64 v[166:167], s[42:43], 0, v[136:137]
	s_add_i32 m0, s7, 0xc000
	ds_read_b128 v[192:195], v145
	ds_read_b128 v[196:199], v145 offset:1024
	ds_read_b128 v[200:203], v145 offset:2048
	ds_read_b128 v[204:207], v145 offset:3072
	ds_read_b128 v[208:211], v145 offset:4096
	ds_read_b128 v[212:215], v145 offset:5120
	ds_read_b128 v[216:219], v145 offset:6144
	ds_read_b128 v[220:223], v145 offset:7168
	global_load_lds_dwordx4 v[166:167], off
	v_lshl_add_u64 v[166:167], s[42:43], 0, v[134:135]
	s_add_i32 m0, s7, 0xe000
	s_nop 0
	global_load_lds_dwordx4 v[166:167], off
	s_waitcnt vmcnt(8)
	s_waitcnt lgkmcnt(0)
	s_barrier
	s_setprio 1
	s_waitcnt lgkmcnt(0)
	v_mfma_f32_16x16x32_bf16 v[124:127], v[138:141], v[192:195], 0
	v_mfma_f32_16x16x32_bf16 v[120:123], v[150:153], v[192:195], 0
	v_mfma_f32_16x16x32_bf16 v[116:119], v[138:141], v[200:203], 0
	v_mfma_f32_16x16x32_bf16 v[108:111], v[150:153], v[200:203], 0
	v_mfma_f32_16x16x32_bf16 v[100:103], v[138:141], v[208:211], 0
	v_mfma_f32_16x16x32_bf16 v[92:95], v[150:153], v[208:211], 0
	v_mfma_f32_16x16x32_bf16 v[84:87], v[138:141], v[216:219], 0
	v_mfma_f32_16x16x32_bf16 v[76:79], v[150:153], v[216:219], 0
	v_mfma_f32_16x16x32_bf16 v[124:127], v[146:149], v[196:199], v[124:127]
	v_mfma_f32_16x16x32_bf16 v[120:123], v[154:157], v[196:199], v[120:123]
	v_mfma_f32_16x16x32_bf16 v[116:119], v[146:149], v[204:207], v[116:119]
	v_mfma_f32_16x16x32_bf16 v[108:111], v[154:157], v[204:207], v[108:111]
	v_mfma_f32_16x16x32_bf16 v[100:103], v[146:149], v[212:215], v[100:103]
	v_mfma_f32_16x16x32_bf16 v[92:95], v[154:157], v[212:215], v[92:95]
	v_mfma_f32_16x16x32_bf16 v[84:87], v[146:149], v[220:223], v[84:87]
	v_mfma_f32_16x16x32_bf16 v[76:79], v[154:157], v[220:223], v[76:79]
	s_setprio 0
	s_setprio 1
	v_mfma_f32_16x16x32_bf16 v[112:115], v[158:161], v[192:195], 0
	v_mfma_f32_16x16x32_bf16 v[104:107], v[170:173], v[192:195], 0
	v_mfma_f32_16x16x32_bf16 v[96:99], v[158:161], v[200:203], 0
	v_mfma_f32_16x16x32_bf16 v[88:91], v[170:173], v[200:203], 0
	v_mfma_f32_16x16x32_bf16 v[80:83], v[158:161], v[208:211], 0
	v_mfma_f32_16x16x32_bf16 v[72:75], v[170:173], v[208:211], 0
	v_mfma_f32_16x16x32_bf16 v[68:71], v[158:161], v[216:219], 0
	v_mfma_f32_16x16x32_bf16 v[64:67], v[170:173], v[216:219], 0
	v_mfma_f32_16x16x32_bf16 v[112:115], v[162:165], v[196:199], v[112:115]
	v_mfma_f32_16x16x32_bf16 v[104:107], v[188:191], v[196:199], v[104:107]
	v_mfma_f32_16x16x32_bf16 v[96:99], v[162:165], v[204:207], v[96:99]
	v_mfma_f32_16x16x32_bf16 v[88:91], v[188:191], v[204:207], v[88:91]
	v_mfma_f32_16x16x32_bf16 v[80:83], v[162:165], v[212:215], v[80:83]
	v_mfma_f32_16x16x32_bf16 v[72:75], v[188:191], v[212:215], v[72:75]
	v_mfma_f32_16x16x32_bf16 v[68:71], v[162:165], v[220:223], v[68:71]
	v_mfma_f32_16x16x32_bf16 v[64:67], v[188:191], v[220:223], v[64:67]
	s_setprio 0
	s_barrier
	s_add_i32 s59, s59, s6
	v_lshl_add_u64 v[166:167], s[44:45], 0, v[168:169]
	s_mov_b32 m0, s59
	ds_read_b128 v[192:195], v145 offset:16384
	ds_read_b128 v[196:199], v145 offset:17408
	ds_read_b128 v[200:203], v145 offset:18432
	ds_read_b128 v[204:207], v145 offset:19456
	ds_read_b128 v[208:211], v145 offset:20480
	ds_read_b128 v[212:215], v145 offset:21504
	ds_read_b128 v[216:219], v145 offset:22528
	ds_read_b128 v[220:223], v145 offset:23552
	global_load_lds_dwordx4 v[166:167], off
	s_add_i32 m0, s59, 0x2000
	s_add_u32 s60, s44, 0x40000
	v_lshl_add_u64 v[178:179], s[44:45], 0, v[128:129]
	s_addc_u32 s61, s45, 0
	s_add_i32 s59, s62, s6
	global_load_lds_dwordx4 v[178:179], off
	v_lshl_add_u64 v[224:225], s[60:61], 0, v[168:169]
	s_mov_b32 m0, s59
	v_lshl_add_u64 v[234:235], s[46:47], 0, v[130:131]
	global_load_lds_dwordx4 v[224:225], off
	v_lshl_add_u64 v[224:225], s[60:61], 0, v[128:129]
	s_add_i32 m0, s59, 0x2000
	s_nop 0
	global_load_lds_dwordx4 v[224:225], off
	v_lshl_add_u64 v[224:225], s[46:47], 0, v[132:133]
	s_mov_b32 m0, s7
	s_nop 0
	global_load_lds_dwordx4 v[224:225], off
	s_mov_b32 m0, s34
	s_nop 0
	global_load_lds_dwordx4 v[234:235], off
	s_waitcnt vmcnt(8)
	s_waitcnt lgkmcnt(0)
	s_barrier
; #define PG8_STAGE(bufoff, gbase, voff) do { _Pragma("unroll") for (int _i = 0; _i < 2; ++_i) \
;         __builtin_amdgcn_global_load_lds((const unsigned*)((const char*)(gbase) + (voff)[_i]), (PG8_LAS unsigned*)(lds + (bufoff) + ldsw + _i * 8192), 16, 0, 0); } while (0)
; #define PG8_LDA(dst, b, h) do { _Pragma("unroll") for (int m = 0; m < 4; ++m) _Pragma("unroll") for (int k = 0; k < 2; ++k) dst[m][k] = *(const PG8_LAS bf16x8*)(lds + PG8_SA(b, h) + aoff + m * 2048 + k * 1024); } while (0)
; #define PG8_LDB(dst, b, h) do { _Pragma("unroll") for (int n = 0; n < 2; ++n) _Pragma("unroll") for (int k = 0; k < 2; ++k) dst[n][k] = *(const PG8_LAS bf16x8*)(lds + PG8_SB(b, h) + boff + n * 2048 + k * 1024); } while (0)
; #define PG8_MMA(ai, bj, At, Bt) do { __builtin_amdgcn_s_setprio(1); _Pragma("unroll") for (int m = 0; m < 4; ++m) _Pragma("unroll") for (int n = 0; n < 2; ++n) _Pragma("unroll") for (int k = 0; k < 2; ++k) \
;         acc[ai][bj][m][n] = __builtin_amdgcn_mfma_f32_16x16x32_bf16(Bt[n][k], At[m][k], acc[ai][bj][m][n], 0, 0, 0); __builtin_amdgcn_s_setprio(0); } while (0)
; #define PG8_WAIT_V(n) asm volatile("s_waitcnt vmcnt(" #n ")" ::: "memory")
; template <class Epi, class Sched, bool ALIGN_EPI = false, bool SP2 = false>
; __device__ __forceinline__ void gemm_phase(PG8_LAS unsigned char* lds, const Gemm g, const Sched& S, const Epi& E) {
;     ...
;             PG8_LDB(B0, 0, 0); PG8_LDB(B1, 0, 1); PG8_SCHED; PG8_LDA(At, 0, 0); PG8_STAGE(PG8_SA(1, 1), a1 + hstepA, voffA);
;             PG8_WAIT_V(8); PG8_WAIT_L(0); PG8_BAR; PG8_MMA(0, 0, At, B0); PG8_MMA(0, 1, At, B1); PG8_BAR; PG8_SCHED;
;             PG8_LDA(At, 0, 1); PG8_STAGE(PG8_SB(0, 0), b2, voffB); PG8_STAGE(PG8_SB(0, 1), b2 + hstep, voffB); PG8_STAGE(PG8_SA(0, 0), a2, voffA);
;             PG8_WAIT_V(8); PG8_WAIT_L(0); PG8_BAR; PG8_MMA(1, 0, At, B0); PG8_MMA(1, 1, At, B1); PG8_BAR; PG8_SCHED;
;             PG8_LDB(B0, 1, 0); PG8_LDB(B1, 1, 1); PG8_SCHED; PG8_LDA(At, 1, 0); PG8_STAGE(PG8_SA(0, 1), a2 + hstepA, voffA);
;             PG8_WAIT_V(8); PG8_WAIT_L(0); PG8_BAR; PG8_MMA(0, 0, At, B0); PG8_MMA(0, 1, At, B1); PG8_BAR; PG8_SCHED;
;             PG8_LDA(At, 1, 1); PG8_STAGE(PG8_SB(1, 0), b3, voffB); PG8_STAGE(PG8_SB(1, 1), b3 + hstep, voffB); PG8_STAGE(PG8_SA(1, 0), a3, voffA);
;             PG8_WAIT_V(8); PG8_WAIT_L(0); PG8_BAR; PG8_MMA(1, 0, At, B0); PG8_MMA(1, 1, At, B1); PG8_BAR; PG8_SCHED;
	s_setprio 1
	s_waitcnt lgkmcnt(0)
	v_mfma_f32_16x16x32_bf16 v[60:63], v[138:141], v[192:195], 0
	v_mfma_f32_16x16x32_bf16 v[56:59], v[150:153], v[192:195], 0
	v_mfma_f32_16x16x32_bf16 v[52:55], v[138:141], v[200:203], 0
	v_mfma_f32_16x16x32_bf16 v[44:47], v[150:153], v[200:203], 0
	v_mfma_f32_16x16x32_bf16 v[36:39], v[138:141], v[208:211], 0
	v_mfma_f32_16x16x32_bf16 v[28:31], v[150:153], v[208:211], 0
	v_mfma_f32_16x16x32_bf16 v[20:23], v[138:141], v[216:219], 0
	v_mfma_f32_16x16x32_bf16 v[12:15], v[150:153], v[216:219], 0
	v_mfma_f32_16x16x32_bf16 v[60:63], v[146:149], v[196:199], v[60:63]
	v_mfma_f32_16x16x32_bf16 v[56:59], v[154:157], v[196:199], v[56:59]
	v_mfma_f32_16x16x32_bf16 v[52:55], v[146:149], v[204:207], v[52:55]
	v_mfma_f32_16x16x32_bf16 v[44:47], v[154:157], v[204:207], v[44:47]
	v_mfma_f32_16x16x32_bf16 v[36:39], v[146:149], v[212:215], v[36:39]
	v_mfma_f32_16x16x32_bf16 v[28:31], v[154:157], v[212:215], v[28:31]
	v_mfma_f32_16x16x32_bf16 v[20:23], v[146:149], v[220:223], v[20:23]
	v_mfma_f32_16x16x32_bf16 v[12:15], v[154:157], v[220:223], v[12:15]
	s_setprio 0
	s_setprio 1
	v_mfma_f32_16x16x32_bf16 v[48:51], v[158:161], v[192:195], 0
	v_mfma_f32_16x16x32_bf16 v[40:43], v[170:173], v[192:195], 0
	v_mfma_f32_16x16x32_bf16 v[32:35], v[158:161], v[200:203], 0
	v_mfma_f32_16x16x32_bf16 v[24:27], v[170:173], v[200:203], 0
	v_mfma_f32_16x16x32_bf16 v[16:19], v[158:161], v[208:211], 0
	v_mfma_f32_16x16x32_bf16 v[8:11], v[170:173], v[208:211], 0
	v_mfma_f32_16x16x32_bf16 v[4:7], v[158:161], v[216:219], 0
	v_mfma_f32_16x16x32_bf16 v[0:3], v[170:173], v[216:219], 0
	v_mfma_f32_16x16x32_bf16 v[48:51], v[162:165], v[196:199], v[48:51]
	v_mfma_f32_16x16x32_bf16 v[40:43], v[188:191], v[196:199], v[40:43]
	v_mfma_f32_16x16x32_bf16 v[32:35], v[162:165], v[204:207], v[32:35]
	v_mfma_f32_16x16x32_bf16 v[24:27], v[188:191], v[204:207], v[24:27]
	v_mfma_f32_16x16x32_bf16 v[16:19], v[162:165], v[212:215], v[16:19]
	v_mfma_f32_16x16x32_bf16 v[8:11], v[188:191], v[212:215], v[8:11]
	v_mfma_f32_16x16x32_bf16 v[4:7], v[162:165], v[220:223], v[4:7]
	v_mfma_f32_16x16x32_bf16 v[0:3], v[188:191], v[220:223], v[0:3]
	s_setprio 0
	s_barrier
	s_add_i32 s59, 0, 0x18000
	s_add_i32 s60, 0, 0x1c000
	v_add_u32_e32 v154, s59, v143
	v_add_u32_e32 v188, s60, v143
	ds_read_b128 v[138:141], v154
	ds_read_b128 v[146:149], v154 offset:1024
	ds_read_b128 v[150:153], v154 offset:2048
	ds_read_b128 v[154:157], v154 offset:3072
	ds_read_b128 v[158:161], v188
	ds_read_b128 v[162:165], v188 offset:1024
	ds_read_b128 v[170:173], v188 offset:2048
	ds_read_b128 v[188:191], v188 offset:3072
	s_add_u32 s46, s46, 0x40000
	s_addc_u32 s47, s47, 0
	s_mov_b32 m0, s35
	v_lshl_add_u64 v[236:237], s[46:47], 0, v[132:133]
	ds_read_b128 v[192:195], v145 offset:32768
	ds_read_b128 v[196:199], v145 offset:33792
	ds_read_b128 v[200:203], v145 offset:34816
	ds_read_b128 v[204:207], v145 offset:35840
	ds_read_b128 v[208:211], v145 offset:36864
	ds_read_b128 v[212:215], v145 offset:37888
	ds_read_b128 v[216:219], v145 offset:38912
	ds_read_b128 v[220:223], v145 offset:39936
	global_load_lds_dwordx4 v[236:237], off
	v_lshl_add_u64 v[236:237], s[46:47], 0, v[130:131]
	s_mov_b32 m0, s48
	s_nop 0
	global_load_lds_dwordx4 v[236:237], off
	s_waitcnt vmcnt(8)
	s_waitcnt lgkmcnt(0)
	s_barrier
	s_setprio 1
	s_waitcnt lgkmcnt(0)
	v_mfma_f32_16x16x32_bf16 v[124:127], v[138:141], v[192:195], v[124:127]
	v_mfma_f32_16x16x32_bf16 v[120:123], v[150:153], v[192:195], v[120:123]
	v_mfma_f32_16x16x32_bf16 v[116:119], v[138:141], v[200:203], v[116:119]
	v_mfma_f32_16x16x32_bf16 v[108:111], v[150:153], v[200:203], v[108:111]
	v_mfma_f32_16x16x32_bf16 v[100:103], v[138:141], v[208:211], v[100:103]
	v_mfma_f32_16x16x32_bf16 v[92:95], v[150:153], v[208:211], v[92:95]
	v_mfma_f32_16x16x32_bf16 v[84:87], v[138:141], v[216:219], v[84:87]
	v_mfma_f32_16x16x32_bf16 v[76:79], v[150:153], v[216:219], v[76:79]
	v_mfma_f32_16x16x32_bf16 v[124:127], v[146:149], v[196:199], v[124:127]
	v_mfma_f32_16x16x32_bf16 v[120:123], v[154:157], v[196:199], v[120:123]
	v_mfma_f32_16x16x32_bf16 v[116:119], v[146:149], v[204:207], v[116:119]
	v_mfma_f32_16x16x32_bf16 v[108:111], v[154:157], v[204:207], v[108:111]
	v_mfma_f32_16x16x32_bf16 v[100:103], v[146:149], v[212:215], v[100:103]
	v_mfma_f32_16x16x32_bf16 v[92:95], v[154:157], v[212:215], v[92:95]
	v_mfma_f32_16x16x32_bf16 v[84:87], v[146:149], v[220:223], v[84:87]
	v_mfma_f32_16x16x32_bf16 v[76:79], v[154:157], v[220:223], v[76:79]
	s_setprio 0
	s_setprio 1
	v_mfma_f32_16x16x32_bf16 v[112:115], v[158:161], v[192:195], v[112:115]
	v_mfma_f32_16x16x32_bf16 v[104:107], v[170:173], v[192:195], v[104:107]
	v_mfma_f32_16x16x32_bf16 v[96:99], v[158:161], v[200:203], v[96:99]
	v_mfma_f32_16x16x32_bf16 v[88:91], v[170:173], v[200:203], v[88:91]
	v_mfma_f32_16x16x32_bf16 v[80:83], v[158:161], v[208:211], v[80:83]
	v_mfma_f32_16x16x32_bf16 v[72:75], v[170:173], v[208:211], v[72:75]
	v_mfma_f32_16x16x32_bf16 v[68:71], v[158:161], v[216:219], v[68:71]
	v_mfma_f32_16x16x32_bf16 v[64:67], v[170:173], v[216:219], v[64:67]
	v_mfma_f32_16x16x32_bf16 v[112:115], v[162:165], v[196:199], v[112:115]
	v_mfma_f32_16x16x32_bf16 v[104:107], v[188:191], v[196:199], v[104:107]
	v_mfma_f32_16x16x32_bf16 v[96:99], v[162:165], v[204:207], v[96:99]
	v_mfma_f32_16x16x32_bf16 v[88:91], v[188:191], v[204:207], v[88:91]
	v_mfma_f32_16x16x32_bf16 v[80:83], v[162:165], v[212:215], v[80:83]
	v_mfma_f32_16x16x32_bf16 v[72:75], v[188:191], v[212:215], v[72:75]
	v_mfma_f32_16x16x32_bf16 v[68:71], v[162:165], v[220:223], v[68:71]
	v_mfma_f32_16x16x32_bf16 v[64:67], v[188:191], v[220:223], v[64:67]
	s_setprio 0
	s_barrier
; #define PG8_STAGE(bufoff, gbase, voff) do { _Pragma("unroll") for (int _i = 0; _i < 2; ++_i) \
;         __builtin_amdgcn_global_load_lds((const unsigned*)((const char*)(gbase) + (voff)[_i]), (PG8_LAS unsigned*)(lds + (bufoff) + ldsw + _i * 8192), 16, 0, 0); } while (0)
; #define PG8_LDA(dst, b, h) do { _Pragma("unroll") for (int m = 0; m < 4; ++m) _Pragma("unroll") for (int k = 0; k < 2; ++k) dst[m][k] = *(const PG8_LAS bf16x8*)(lds + PG8_SA(b, h) + aoff + m * 2048 + k * 1024); } while (0)
; #define PG8_LDB(dst, b, h) do { _Pragma("unroll") for (int n = 0; n < 2; ++n) _Pragma("unroll") for (int k = 0; k < 2; ++k) dst[n][k] = *(const PG8_LAS bf16x8*)(lds + PG8_SB(b, h) + boff + n * 2048 + k * 1024); } while (0)
; #define PG8_MMA(ai, bj, At, Bt) do { __builtin_amdgcn_s_setprio(1); _Pragma("unroll") for (int m = 0; m < 4; ++m) _Pragma("unroll") for (int n = 0; n < 2; ++n) _Pragma("unroll") for (int k = 0; k < 2; ++k) \
;         acc[ai][bj][m][n] = __builtin_amdgcn_mfma_f32_16x16x32_bf16(Bt[n][k], At[m][k], acc[ai][bj][m][n], 0, 0, 0); __builtin_amdgcn_s_setprio(0); } while (0)
; #define PG8_WAIT_V(n) asm volatile("s_waitcnt vmcnt(" #n ")" ::: "memory")
; #define PG8_WAIT_L(n) asm volatile("s_waitcnt lgkmcnt(" #n ")" ::: "memory")
; #define PG8_BAR __builtin_amdgcn_s_barrier()
; #define PG8_SCHED __builtin_amdgcn_sched_barrier(0)
; template <class Epi, class Sched, bool ALIGN_EPI = false, bool SP2 = false>
; __device__ __forceinline__ void gemm_phase(PG8_LAS unsigned char* lds, const Gemm g, const Sched& S, const Epi& E) {
;     ...
;             PG8_LDB(B0, 1, 0); PG8_LDB(B1, 1, 1); PG8_SCHED; PG8_LDA(At, 1, 0); PG8_STAGE(PG8_SA(0, 1), a2 + hstepA, voffA);
;             PG8_WAIT_V(8); PG8_WAIT_L(0); PG8_BAR; PG8_MMA(0, 0, At, B0); PG8_MMA(0, 1, At, B1); PG8_BAR; PG8_SCHED;
;             PG8_LDA(At, 1, 1); PG8_STAGE(PG8_SB(1, 0), b3, voffB); PG8_STAGE(PG8_SB(1, 1), b3 + hstep, voffB); PG8_STAGE(PG8_SA(1, 0), a3, voffA);
;             PG8_WAIT_V(8); PG8_WAIT_L(0); PG8_BAR; PG8_MMA(1, 0, At, B0); PG8_MMA(1, 1, At, B1); PG8_BAR; PG8_SCHED;
	s_add_i32 s46, s59, s6
	v_lshl_add_u64 v[166:167], v[166:167], 0, s[30:31]
	s_mov_b32 m0, s46
	ds_read_b128 v[192:195], v145 offset:49152
	ds_read_b128 v[196:199], v145 offset:50176
	ds_read_b128 v[200:203], v145 offset:51200
	ds_read_b128 v[204:207], v145 offset:52224
	ds_read_b128 v[208:211], v145 offset:53248
	ds_read_b128 v[212:215], v145 offset:54272
	ds_read_b128 v[216:219], v145 offset:55296
	ds_read_b128 v[220:223], v145 offset:56320
	global_load_lds_dwordx4 v[166:167], off
	s_add_i32 m0, s46, 0x2000
	s_add_u32 s44, s44, 0x40080
	v_lshl_add_u64 v[166:167], v[178:179], 0, s[30:31]
	s_addc_u32 s45, s45, 0
	s_add_i32 s46, s60, s6
	global_load_lds_dwordx4 v[166:167], off
	v_lshl_add_u64 v[166:167], s[44:45], 0, v[168:169]
	s_mov_b32 m0, s46
	s_nop 0
	global_load_lds_dwordx4 v[166:167], off
	v_lshl_add_u64 v[166:167], s[44:45], 0, v[128:129]
	s_add_i32 m0, s46, 0x2000
	s_nop 0
	global_load_lds_dwordx4 v[166:167], off
	v_lshl_add_u64 v[166:167], v[224:225], 0, s[30:31]
	s_mov_b32 m0, s49
	s_nop 0
	global_load_lds_dwordx4 v[166:167], off
	v_lshl_add_u64 v[166:167], v[234:235], 0, s[30:31]
	s_mov_b32 m0, s50
	s_nop 0
	global_load_lds_dwordx4 v[166:167], off
	s_waitcnt vmcnt(8)
	s_waitcnt lgkmcnt(0)
	s_barrier
	s_setprio 1
	s_waitcnt lgkmcnt(0)
	v_mfma_f32_16x16x32_bf16 v[60:63], v[138:141], v[192:195], v[60:63]
	v_mfma_f32_16x16x32_bf16 v[56:59], v[150:153], v[192:195], v[56:59]
	v_mfma_f32_16x16x32_bf16 v[52:55], v[138:141], v[200:203], v[52:55]
	v_mfma_f32_16x16x32_bf16 v[44:47], v[150:153], v[200:203], v[44:47]
	v_mfma_f32_16x16x32_bf16 v[36:39], v[138:141], v[208:211], v[36:39]
	v_mfma_f32_16x16x32_bf16 v[28:31], v[150:153], v[208:211], v[28:31]
	v_mfma_f32_16x16x32_bf16 v[20:23], v[138:141], v[216:219], v[20:23]
	v_mfma_f32_16x16x32_bf16 v[12:15], v[150:153], v[216:219], v[12:15]
	v_mfma_f32_16x16x32_bf16 v[60:63], v[146:149], v[196:199], v[60:63]
	v_mfma_f32_16x16x32_bf16 v[56:59], v[154:157], v[196:199], v[56:59]
	v_mfma_f32_16x16x32_bf16 v[52:55], v[146:149], v[204:207], v[52:55]
	v_mfma_f32_16x16x32_bf16 v[44:47], v[154:157], v[204:207], v[44:47]
	v_mfma_f32_16x16x32_bf16 v[36:39], v[146:149], v[212:215], v[36:39]
	v_mfma_f32_16x16x32_bf16 v[28:31], v[154:157], v[212:215], v[28:31]
	v_mfma_f32_16x16x32_bf16 v[20:23], v[146:149], v[220:223], v[20:23]
	v_mfma_f32_16x16x32_bf16 v[12:15], v[154:157], v[220:223], v[12:15]
	s_setprio 0
	s_setprio 1
	v_mfma_f32_16x16x32_bf16 v[48:51], v[158:161], v[192:195], v[48:51]
	v_mfma_f32_16x16x32_bf16 v[40:43], v[170:173], v[192:195], v[40:43]
	v_mfma_f32_16x16x32_bf16 v[32:35], v[158:161], v[200:203], v[32:35]
	v_mfma_f32_16x16x32_bf16 v[24:27], v[170:173], v[200:203], v[24:27]
	v_mfma_f32_16x16x32_bf16 v[16:19], v[158:161], v[208:211], v[16:19]
	v_mfma_f32_16x16x32_bf16 v[8:11], v[170:173], v[208:211], v[8:11]
	v_mfma_f32_16x16x32_bf16 v[4:7], v[158:161], v[216:219], v[4:7]
	v_mfma_f32_16x16x32_bf16 v[0:3], v[170:173], v[216:219], v[0:3]
	v_mfma_f32_16x16x32_bf16 v[48:51], v[162:165], v[196:199], v[48:51]
	v_mfma_f32_16x16x32_bf16 v[40:43], v[188:191], v[196:199], v[40:43]
	v_mfma_f32_16x16x32_bf16 v[32:35], v[162:165], v[204:207], v[32:35]
	v_mfma_f32_16x16x32_bf16 v[24:27], v[188:191], v[204:207], v[24:27]
	v_mfma_f32_16x16x32_bf16 v[16:19], v[162:165], v[212:215], v[16:19]
	v_mfma_f32_16x16x32_bf16 v[8:11], v[188:191], v[212:215], v[8:11]
	v_mfma_f32_16x16x32_bf16 v[4:7], v[162:165], v[220:223], v[4:7]
	v_mfma_f32_16x16x32_bf16 v[0:3], v[188:191], v[220:223], v[0:3]
	s_setprio 0
	s_barrier
	s_add_i32 s58, s58, 2
	s_add_u32 s56, s56, 0x100
	s_addc_u32 s57, s57, 0
	s_add_u32 s42, s42, 0x100
	s_addc_u32 s43, s43, 0

; #define PG8_STAGE(bufoff, gbase, voff) do { _Pragma("unroll") for (int _i = 0; _i < 2; ++_i) \
;         __builtin_amdgcn_global_load_lds((const unsigned*)((const char*)(gbase) + (voff)[_i]), (PG8_LAS unsigned*)(lds + (bufoff) + ldsw + _i * 8192), 16, 0, 0); } while (0)
; #define PG8_LDA(dst, b, h) do { _Pragma("unroll") for (int m = 0; m < 4; ++m) _Pragma("unroll") for (int k = 0; k < 2; ++k) dst[m][k] = *(const PG8_LAS bf16x8*)(lds + PG8_SA(b, h) + aoff + m * 2048 + k * 1024); } while (0)
; template <class Epi, class Sched, bool ALIGN_EPI = false, bool SP2 = false>
; __device__ __forceinline__ void gemm_phase(PG8_LAS unsigned char* lds, const Gemm g, const Sched& S, const Epi& E) {
;     ...
;         const bool has_next = S.next(ui + 1, nxt);
;         const char* nA = has_next ? (const char*)g.A + (size_t)nxt.pm * tstepA : cA; const char* nB = has_next ? (const char*)g.Bt + (size_t)nxt.pn * tstep : cB;
;         for (int t = 0; t < nt; t += 2) {
;             const bool last = (t == nt - 2);
;             const char* a1 = cA + (size_t)(t + 1) * kstepA;
;             const char* a2 = last ? nA : cA + (size_t)(t + 2) * kstepA; const char* b2 = last ? nB : cB + (size_t)(t + 2) * kstep;
;             const char* a3 = a2 + kstepA; const char* b3 = b2 + kstep;
;             if (last && has_next) S.a_ready(nxt);
;             if constexpr (SP2) {
;             PG8_LDB(B0, 0, 0); PG8_LDB(B1, 0, 1); PG8_SCHED; PG8_LDA(At, 0, 0); PG8_STAGE(PG8_SA(1, 1), a1 + hstepA, voffA);
;             PG8_WAIT_V(8); PG8_WAIT_L(0); PG8_BAR; PG8_MMA(0, 0, At, B0); PG8_MMA(0, 1, At, B1); PG8_BAR; PG8_SCHED;
;             PG8_LDA(At, 0, 1); PG8_STAGE(PG8_SB(0, 0), b2, voffB); PG8_STAGE(PG8_SB(0, 1), b2 + hstep, voffB); PG8_STAGE(PG8_SA(0, 0), a2, voffA);
;             PG8_WAIT_V(8); PG8_WAIT_L(0); PG8_BAR; PG8_MMA(1, 0, At, B0); PG8_MMA(1, 1, At, B1); PG8_BAR; PG8_SCHED;
;             PG8_LDB(B0, 1, 0); PG8_LDB(B1, 1, 1); PG8_SCHED; PG8_LDA(At, 1, 0); PG8_STAGE(PG8_SA(0, 1), a2 + hstepA, voffA);
;             PG8_WAIT_V(8); PG8_WAIT_L(0); PG8_BAR; PG8_MMA(0, 0, At, B0); PG8_MMA(0, 1, At, B1); PG8_BAR; PG8_SCHED;
;             PG8_LDA(At, 1, 1); PG8_STAGE(PG8_SB(1, 0), b3, voffB); PG8_STAGE(PG8_SB(1, 1), b3 + hstep, voffB); PG8_STAGE(PG8_SA(1, 0), a3, voffA);
;             PG8_WAIT_V(8); PG8_WAIT_L(0); PG8_BAR; PG8_MMA(1, 0, At, B0); PG8_MMA(1, 1, At, B1); PG8_BAR; PG8_SCHED;
.LBB0_433:
	s_ashr_i32 s41, s40, 31
	s_lshl_b64 s[42:43], s[40:41], 19
	s_add_u32 s42, s20, s42
	s_addc_u32 s43, s21, s43
	s_and_b64 s[44:45], s[36:37], exec
	s_cselect_b32 s41, s43, s39
	s_cselect_b32 s54, s42, s38
	s_ashr_i32 s27, s26, 31
	s_lshl_b64 s[44:45], s[26:27], 19
	s_add_u32 s44, s3, s44
	s_addc_u32 s45, s6, s45
	s_and_b64 s[46:47], s[36:37], exec
	s_cselect_b32 s27, s45, s5
	s_cselect_b32 s55, s44, s4
	s_add_u32 s56, s4, 0x100
	s_addc_u32 s57, s5, 0
	s_add_u32 s4, s38, 0x40080
	s_addc_u32 s5, s39, 0
	s_mov_b32 s58, -2
	s_add_u32 s38, s4, 0xfffc0080
	s_addc_u32 s39, s5, -1
	s_add_i32 s59, 0, 0x10000
	s_cmp_eq_u32 s58, 12
	s_cselect_b32 s47, s41, s39
	s_cselect_b32 s46, s54, s38
	s_cselect_b32 s39, s27, s57
	s_cselect_b32 s38, s55, s56
	s_add_i32 s62, 0, 0x14000
	v_add_u32_e32 v154, s59, v143
	v_add_u32_e32 v166, s62, v143
	ds_read_b128 v[138:141], v154
	ds_read_b128 v[146:149], v154 offset:1024
	ds_read_b128 v[150:153], v154 offset:2048
	ds_read_b128 v[154:157], v154 offset:3072
	ds_read_b128 v[158:161], v166
	ds_read_b128 v[162:165], v166 offset:1024
	ds_read_b128 v[188:191], v166 offset:2048
	ds_read_b128 v[192:195], v166 offset:3072
	v_lshl_add_u64 v[166:167], s[4:5], 0, v[136:137]
	s_add_i32 m0, s2, 0xc000
	ds_read_b128 v[196:199], v145
	ds_read_b128 v[200:203], v145 offset:1024
	ds_read_b128 v[204:207], v145 offset:2048
	ds_read_b128 v[208:211], v145 offset:3072
	ds_read_b128 v[212:215], v145 offset:4096
	ds_read_b128 v[216:219], v145 offset:5120
	ds_read_b128 v[220:223], v145 offset:6144
	ds_read_b128 v[234:237], v145 offset:7168
	global_load_lds_dwordx4 v[166:167], off
	v_lshl_add_u64 v[166:167], s[4:5], 0, v[134:135]
	s_add_i32 m0, s2, 0xe000
	s_nop 0
	global_load_lds_dwordx4 v[166:167], off
	s_waitcnt vmcnt(8)
	s_waitcnt lgkmcnt(0)
	s_barrier
	s_setprio 1
	s_waitcnt lgkmcnt(0)
	v_mfma_f32_16x16x32_bf16 v[124:127], v[138:141], v[196:199], 0
	v_mfma_f32_16x16x32_bf16 v[120:123], v[150:153], v[196:199], 0
	v_mfma_f32_16x16x32_bf16 v[108:111], v[138:141], v[204:207], 0
	v_mfma_f32_16x16x32_bf16 v[104:107], v[150:153], v[204:207], 0
	v_mfma_f32_16x16x32_bf16 v[92:95], v[138:141], v[212:215], 0
	v_mfma_f32_16x16x32_bf16 v[88:91], v[150:153], v[212:215], 0
	v_mfma_f32_16x16x32_bf16 v[76:79], v[138:141], v[220:223], 0
	v_mfma_f32_16x16x32_bf16 v[72:75], v[150:153], v[220:223], 0
	v_mfma_f32_16x16x32_bf16 v[124:127], v[146:149], v[200:203], v[124:127]
	v_mfma_f32_16x16x32_bf16 v[120:123], v[154:157], v[200:203], v[120:123]
	v_mfma_f32_16x16x32_bf16 v[108:111], v[146:149], v[208:211], v[108:111]
	v_mfma_f32_16x16x32_bf16 v[104:107], v[154:157], v[208:211], v[104:107]
	v_mfma_f32_16x16x32_bf16 v[92:95], v[146:149], v[216:219], v[92:95]
	v_mfma_f32_16x16x32_bf16 v[88:91], v[154:157], v[216:219], v[88:91]
	v_mfma_f32_16x16x32_bf16 v[76:79], v[146:149], v[234:237], v[76:79]
	v_mfma_f32_16x16x32_bf16 v[72:75], v[154:157], v[234:237], v[72:75]
	s_setprio 0
	s_setprio 1
	v_mfma_f32_16x16x32_bf16 v[116:119], v[158:161], v[196:199], 0
	v_mfma_f32_16x16x32_bf16 v[112:115], v[188:191], v[196:199], 0
	v_mfma_f32_16x16x32_bf16 v[100:103], v[158:161], v[204:207], 0
	v_mfma_f32_16x16x32_bf16 v[96:99], v[188:191], v[204:207], 0
	v_mfma_f32_16x16x32_bf16 v[84:87], v[158:161], v[212:215], 0
	v_mfma_f32_16x16x32_bf16 v[80:83], v[188:191], v[212:215], 0
	v_mfma_f32_16x16x32_bf16 v[68:71], v[158:161], v[220:223], 0
	v_mfma_f32_16x16x32_bf16 v[64:67], v[188:191], v[220:223], 0
	v_mfma_f32_16x16x32_bf16 v[116:119], v[162:165], v[200:203], v[116:119]
	v_mfma_f32_16x16x32_bf16 v[112:115], v[192:195], v[200:203], v[112:115]
	v_mfma_f32_16x16x32_bf16 v[100:103], v[162:165], v[208:211], v[100:103]
	v_mfma_f32_16x16x32_bf16 v[96:99], v[192:195], v[208:211], v[96:99]
	v_mfma_f32_16x16x32_bf16 v[84:87], v[162:165], v[216:219], v[84:87]
	v_mfma_f32_16x16x32_bf16 v[80:83], v[192:195], v[216:219], v[80:83]
	v_mfma_f32_16x16x32_bf16 v[68:71], v[162:165], v[234:237], v[68:71]
	v_mfma_f32_16x16x32_bf16 v[64:67], v[192:195], v[234:237], v[64:67]
	s_setprio 0
	s_barrier
	s_add_i32 s59, s59, s7
	v_lshl_add_u64 v[166:167], s[38:39], 0, v[168:169]
	s_mov_b32 m0, s59
	ds_read_b128 v[196:199], v145 offset:16384
	ds_read_b128 v[200:203], v145 offset:17408
	ds_read_b128 v[204:207], v145 offset:18432
	ds_read_b128 v[208:211], v145 offset:19456
	ds_read_b128 v[212:215], v145 offset:20480
	ds_read_b128 v[216:219], v145 offset:21504
	ds_read_b128 v[220:223], v145 offset:22528
	ds_read_b128 v[234:237], v145 offset:23552
	global_load_lds_dwordx4 v[166:167], off
	s_add_i32 m0, s59, 0x2000
	s_add_u32 s60, s38, 0x40000
	v_lshl_add_u64 v[170:171], s[38:39], 0, v[128:129]
	s_addc_u32 s61, s39, 0
	s_add_i32 s59, s62, s7
	global_load_lds_dwordx4 v[170:171], off
	v_lshl_add_u64 v[172:173], s[60:61], 0, v[168:169]
	s_mov_b32 m0, s59
	v_lshl_add_u64 v[224:225], s[46:47], 0, v[130:131]
	global_load_lds_dwordx4 v[172:173], off
	v_lshl_add_u64 v[172:173], s[60:61], 0, v[128:129]
	s_add_i32 m0, s59, 0x2000
	s_nop 0
	global_load_lds_dwordx4 v[172:173], off
	v_lshl_add_u64 v[172:173], s[46:47], 0, v[132:133]
	s_mov_b32 m0, s2
	s_nop 0
	global_load_lds_dwordx4 v[172:173], off
	s_mov_b32 m0, s34
	s_nop 0
	global_load_lds_dwordx4 v[224:225], off
	s_waitcnt vmcnt(8)
	s_waitcnt lgkmcnt(0)
	s_barrier
; #define PG8_STAGE(bufoff, gbase, voff) do { _Pragma("unroll") for (int _i = 0; _i < 2; ++_i) \
;         __builtin_amdgcn_global_load_lds((const unsigned*)((const char*)(gbase) + (voff)[_i]), (PG8_LAS unsigned*)(lds + (bufoff) + ldsw + _i * 8192), 16, 0, 0); } while (0)
; #define PG8_LDA(dst, b, h) do { _Pragma("unroll") for (int m = 0; m < 4; ++m) _Pragma("unroll") for (int k = 0; k < 2; ++k) dst[m][k] = *(const PG8_LAS bf16x8*)(lds + PG8_SA(b, h) + aoff + m * 2048 + k * 1024); } while (0)
; #define PG8_LDB(dst, b, h) do { _Pragma("unroll") for (int n = 0; n < 2; ++n) _Pragma("unroll") for (int k = 0; k < 2; ++k) dst[n][k] = *(const PG8_LAS bf16x8*)(lds + PG8_SB(b, h) + boff + n * 2048 + k * 1024); } while (0)
; #define PG8_MMA(ai, bj, At, Bt) do { __builtin_amdgcn_s_setprio(1); _Pragma("unroll") for (int m = 0; m < 4; ++m) _Pragma("unroll") for (int n = 0; n < 2; ++n) _Pragma("unroll") for (int k = 0; k < 2; ++k) \
;         acc[ai][bj][m][n] = __builtin_amdgcn_mfma_f32_16x16x32_bf16(Bt[n][k], At[m][k], acc[ai][bj][m][n], 0, 0, 0); __builtin_amdgcn_s_setprio(0); } while (0)
; #define PG8_WAIT_V(n) asm volatile("s_waitcnt vmcnt(" #n ")" ::: "memory")
; template <class Epi, class Sched, bool ALIGN_EPI = false, bool SP2 = false>
; __device__ __forceinline__ void gemm_phase(PG8_LAS unsigned char* lds, const Gemm g, const Sched& S, const Epi& E) {
;     ...
;             PG8_LDB(B0, 0, 0); PG8_LDB(B1, 0, 1); PG8_SCHED; PG8_LDA(At, 0, 0); PG8_STAGE(PG8_SA(1, 1), a1 + hstepA, voffA);
;             PG8_WAIT_V(8); PG8_WAIT_L(0); PG8_BAR; PG8_MMA(0, 0, At, B0); PG8_MMA(0, 1, At, B1); PG8_BAR; PG8_SCHED;
;             PG8_LDA(At, 0, 1); PG8_STAGE(PG8_SB(0, 0), b2, voffB); PG8_STAGE(PG8_SB(0, 1), b2 + hstep, voffB); PG8_STAGE(PG8_SA(0, 0), a2, voffA);
;             PG8_WAIT_V(8); PG8_WAIT_L(0); PG8_BAR; PG8_MMA(1, 0, At, B0); PG8_MMA(1, 1, At, B1); PG8_BAR; PG8_SCHED;
;             PG8_LDB(B0, 1, 0); PG8_LDB(B1, 1, 1); PG8_SCHED; PG8_LDA(At, 1, 0); PG8_STAGE(PG8_SA(0, 1), a2 + hstepA, voffA);
;             PG8_WAIT_V(8); PG8_WAIT_L(0); PG8_BAR; PG8_MMA(0, 0, At, B0); PG8_MMA(0, 1, At, B1); PG8_BAR; PG8_SCHED;
;             PG8_LDA(At, 1, 1); PG8_STAGE(PG8_SB(1, 0), b3, voffB); PG8_STAGE(PG8_SB(1, 1), b3 + hstep, voffB); PG8_STAGE(PG8_SA(1, 0), a3, voffA);
;             PG8_WAIT_V(8); PG8_WAIT_L(0); PG8_BAR; PG8_MMA(1, 0, At, B0); PG8_MMA(1, 1, At, B1); PG8_BAR; PG8_SCHED;
	s_setprio 1
	s_waitcnt lgkmcnt(0)
	v_mfma_f32_16x16x32_bf16 v[60:63], v[138:141], v[196:199], 0
	v_mfma_f32_16x16x32_bf16 v[56:59], v[150:153], v[196:199], 0
	v_mfma_f32_16x16x32_bf16 v[44:47], v[138:141], v[204:207], 0
	v_mfma_f32_16x16x32_bf16 v[40:43], v[150:153], v[204:207], 0
	v_mfma_f32_16x16x32_bf16 v[28:31], v[138:141], v[212:215], 0
	v_mfma_f32_16x16x32_bf16 v[24:27], v[150:153], v[212:215], 0
	v_mfma_f32_16x16x32_bf16 v[12:15], v[138:141], v[220:223], 0
	v_mfma_f32_16x16x32_bf16 v[8:11], v[150:153], v[220:223], 0
	v_mfma_f32_16x16x32_bf16 v[60:63], v[146:149], v[200:203], v[60:63]
	v_mfma_f32_16x16x32_bf16 v[56:59], v[154:157], v[200:203], v[56:59]
	v_mfma_f32_16x16x32_bf16 v[44:47], v[146:149], v[208:211], v[44:47]
	v_mfma_f32_16x16x32_bf16 v[40:43], v[154:157], v[208:211], v[40:43]
	v_mfma_f32_16x16x32_bf16 v[28:31], v[146:149], v[216:219], v[28:31]
	v_mfma_f32_16x16x32_bf16 v[24:27], v[154:157], v[216:219], v[24:27]
	v_mfma_f32_16x16x32_bf16 v[12:15], v[146:149], v[234:237], v[12:15]
	v_mfma_f32_16x16x32_bf16 v[8:11], v[154:157], v[234:237], v[8:11]
	s_setprio 0
	s_setprio 1
	v_mfma_f32_16x16x32_bf16 v[52:55], v[158:161], v[196:199], 0
	v_mfma_f32_16x16x32_bf16 v[48:51], v[188:191], v[196:199], 0
	v_mfma_f32_16x16x32_bf16 v[36:39], v[158:161], v[204:207], 0
	v_mfma_f32_16x16x32_bf16 v[32:35], v[188:191], v[204:207], 0
	v_mfma_f32_16x16x32_bf16 v[20:23], v[158:161], v[212:215], 0
	v_mfma_f32_16x16x32_bf16 v[16:19], v[188:191], v[212:215], 0
	v_mfma_f32_16x16x32_bf16 v[4:7], v[158:161], v[220:223], 0
	v_mfma_f32_16x16x32_bf16 v[0:3], v[188:191], v[220:223], 0
	v_mfma_f32_16x16x32_bf16 v[52:55], v[162:165], v[200:203], v[52:55]
	v_mfma_f32_16x16x32_bf16 v[48:51], v[192:195], v[200:203], v[48:51]
	v_mfma_f32_16x16x32_bf16 v[36:39], v[162:165], v[208:211], v[36:39]
	v_mfma_f32_16x16x32_bf16 v[32:35], v[192:195], v[208:211], v[32:35]
	v_mfma_f32_16x16x32_bf16 v[20:23], v[162:165], v[216:219], v[20:23]
	v_mfma_f32_16x16x32_bf16 v[16:19], v[192:195], v[216:219], v[16:19]
	v_mfma_f32_16x16x32_bf16 v[4:7], v[162:165], v[234:237], v[4:7]
	v_mfma_f32_16x16x32_bf16 v[0:3], v[192:195], v[234:237], v[0:3]
	s_setprio 0
	s_barrier
	s_add_i32 s59, 0, 0x18000
	s_add_i32 s60, 0, 0x1c000
	v_add_u32_e32 v154, s59, v143
	v_add_u32_e32 v178, s60, v143
	ds_read_b128 v[138:141], v154
	ds_read_b128 v[146:149], v154 offset:1024
	ds_read_b128 v[150:153], v154 offset:2048
	ds_read_b128 v[154:157], v154 offset:3072
	ds_read_b128 v[158:161], v178
	ds_read_b128 v[162:165], v178 offset:1024
	ds_read_b128 v[188:191], v178 offset:2048
	ds_read_b128 v[192:195], v178 offset:3072
	s_add_u32 s46, s46, 0x40000
	s_addc_u32 s47, s47, 0
	s_mov_b32 m0, s35
	v_lshl_add_u64 v[238:239], s[46:47], 0, v[132:133]
	ds_read_b128 v[196:199], v145 offset:32768
	ds_read_b128 v[200:203], v145 offset:33792
	ds_read_b128 v[204:207], v145 offset:34816
	ds_read_b128 v[208:211], v145 offset:35840
	ds_read_b128 v[212:215], v145 offset:36864
	ds_read_b128 v[216:219], v145 offset:37888
	ds_read_b128 v[220:223], v145 offset:38912
	ds_read_b128 v[234:237], v145 offset:39936
	global_load_lds_dwordx4 v[238:239], off
	v_lshl_add_u64 v[238:239], s[46:47], 0, v[130:131]
	s_mov_b32 m0, s48
	s_nop 0
	global_load_lds_dwordx4 v[238:239], off
	s_waitcnt vmcnt(8)
	s_waitcnt lgkmcnt(0)
	s_barrier
	s_setprio 1
	s_waitcnt lgkmcnt(0)
	v_mfma_f32_16x16x32_bf16 v[124:127], v[138:141], v[196:199], v[124:127]
	v_mfma_f32_16x16x32_bf16 v[120:123], v[150:153], v[196:199], v[120:123]
	v_mfma_f32_16x16x32_bf16 v[108:111], v[138:141], v[204:207], v[108:111]
	v_mfma_f32_16x16x32_bf16 v[104:107], v[150:153], v[204:207], v[104:107]
	v_mfma_f32_16x16x32_bf16 v[92:95], v[138:141], v[212:215], v[92:95]
	v_mfma_f32_16x16x32_bf16 v[88:91], v[150:153], v[212:215], v[88:91]
	v_mfma_f32_16x16x32_bf16 v[76:79], v[138:141], v[220:223], v[76:79]
	v_mfma_f32_16x16x32_bf16 v[72:75], v[150:153], v[220:223], v[72:75]
	v_mfma_f32_16x16x32_bf16 v[124:127], v[146:149], v[200:203], v[124:127]
	v_mfma_f32_16x16x32_bf16 v[120:123], v[154:157], v[200:203], v[120:123]
	v_mfma_f32_16x16x32_bf16 v[108:111], v[146:149], v[208:211], v[108:111]
	v_mfma_f32_16x16x32_bf16 v[104:107], v[154:157], v[208:211], v[104:107]
	v_mfma_f32_16x16x32_bf16 v[92:95], v[146:149], v[216:219], v[92:95]
	v_mfma_f32_16x16x32_bf16 v[88:91], v[154:157], v[216:219], v[88:91]
	v_mfma_f32_16x16x32_bf16 v[76:79], v[146:149], v[234:237], v[76:79]
	v_mfma_f32_16x16x32_bf16 v[72:75], v[154:157], v[234:237], v[72:75]
	s_setprio 0
	s_setprio 1
	v_mfma_f32_16x16x32_bf16 v[116:119], v[158:161], v[196:199], v[116:119]
	v_mfma_f32_16x16x32_bf16 v[112:115], v[188:191], v[196:199], v[112:115]
	v_mfma_f32_16x16x32_bf16 v[100:103], v[158:161], v[204:207], v[100:103]
	v_mfma_f32_16x16x32_bf16 v[96:99], v[188:191], v[204:207], v[96:99]
	v_mfma_f32_16x16x32_bf16 v[84:87], v[158:161], v[212:215], v[84:87]
	v_mfma_f32_16x16x32_bf16 v[80:83], v[188:191], v[212:215], v[80:83]
	v_mfma_f32_16x16x32_bf16 v[68:71], v[158:161], v[220:223], v[68:71]
	v_mfma_f32_16x16x32_bf16 v[64:67], v[188:191], v[220:223], v[64:67]
	v_mfma_f32_16x16x32_bf16 v[116:119], v[162:165], v[200:203], v[116:119]
	v_mfma_f32_16x16x32_bf16 v[112:115], v[192:195], v[200:203], v[112:115]
	v_mfma_f32_16x16x32_bf16 v[100:103], v[162:165], v[208:211], v[100:103]
	v_mfma_f32_16x16x32_bf16 v[96:99], v[192:195], v[208:211], v[96:99]
	v_mfma_f32_16x16x32_bf16 v[84:87], v[162:165], v[216:219], v[84:87]
	v_mfma_f32_16x16x32_bf16 v[80:83], v[192:195], v[216:219], v[80:83]
	v_mfma_f32_16x16x32_bf16 v[68:71], v[162:165], v[234:237], v[68:71]
	v_mfma_f32_16x16x32_bf16 v[64:67], v[192:195], v[234:237], v[64:67]
	s_setprio 0
	s_barrier
; #define PG8_STAGE(bufoff, gbase, voff) do { _Pragma("unroll") for (int _i = 0; _i < 2; ++_i) \
;         __builtin_amdgcn_global_load_lds((const unsigned*)((const char*)(gbase) + (voff)[_i]), (PG8_LAS unsigned*)(lds + (bufoff) + ldsw + _i * 8192), 16, 0, 0); } while (0)
; #define PG8_LDA(dst, b, h) do { _Pragma("unroll") for (int m = 0; m < 4; ++m) _Pragma("unroll") for (int k = 0; k < 2; ++k) dst[m][k] = *(const PG8_LAS bf16x8*)(lds + PG8_SA(b, h) + aoff + m * 2048 + k * 1024); } while (0)
; #define PG8_LDB(dst, b, h) do { _Pragma("unroll") for (int n = 0; n < 2; ++n) _Pragma("unroll") for (int k = 0; k < 2; ++k) dst[n][k] = *(const PG8_LAS bf16x8*)(lds + PG8_SB(b, h) + boff + n * 2048 + k * 1024); } while (0)
; #define PG8_MMA(ai, bj, At, Bt) do { __builtin_amdgcn_s_setprio(1); _Pragma("unroll") for (int m = 0; m < 4; ++m) _Pragma("unroll") for (int n = 0; n < 2; ++n) _Pragma("unroll") for (int k = 0; k < 2; ++k) \
;         acc[ai][bj][m][n] = __builtin_amdgcn_mfma_f32_16x16x32_bf16(Bt[n][k], At[m][k], acc[ai][bj][m][n], 0, 0, 0); __builtin_amdgcn_s_setprio(0); } while (0)
; #define PG8_WAIT_V(n) asm volatile("s_waitcnt vmcnt(" #n ")" ::: "memory")
; #define PG8_WAIT_L(n) asm volatile("s_waitcnt lgkmcnt(" #n ")" ::: "memory")
; #define PG8_BAR __builtin_amdgcn_s_barrier()
; #define PG8_SCHED __builtin_amdgcn_sched_barrier(0)
; template <class Epi, class Sched, bool ALIGN_EPI = false, bool SP2 = false>
; __device__ __forceinline__ void gemm_phase(PG8_LAS unsigned char* lds, const Gemm g, const Sched& S, const Epi& E) {
;     ...
;             PG8_LDB(B0, 1, 0); PG8_LDB(B1, 1, 1); PG8_SCHED; PG8_LDA(At, 1, 0); PG8_STAGE(PG8_SA(0, 1), a2 + hstepA, voffA);
;             PG8_WAIT_V(8); PG8_WAIT_L(0); PG8_BAR; PG8_MMA(0, 0, At, B0); PG8_MMA(0, 1, At, B1); PG8_BAR; PG8_SCHED;
;             PG8_LDA(At, 1, 1); PG8_STAGE(PG8_SB(1, 0), b3, voffB); PG8_STAGE(PG8_SB(1, 1), b3 + hstep, voffB); PG8_STAGE(PG8_SA(1, 0), a3, voffA);
;             PG8_WAIT_V(8); PG8_WAIT_L(0); PG8_BAR; PG8_MMA(1, 0, At, B0); PG8_MMA(1, 1, At, B1); PG8_BAR; PG8_SCHED;
	s_add_i32 s46, s59, s7
	v_lshl_add_u64 v[166:167], v[166:167], 0, s[30:31]
	s_mov_b32 m0, s46
	ds_read_b128 v[196:199], v145 offset:49152
	ds_read_b128 v[200:203], v145 offset:50176
	ds_read_b128 v[204:207], v145 offset:51200
	ds_read_b128 v[208:211], v145 offset:52224
	ds_read_b128 v[212:215], v145 offset:53248
	ds_read_b128 v[216:219], v145 offset:54272
	ds_read_b128 v[220:223], v145 offset:55296
	ds_read_b128 v[234:237], v145 offset:56320
	global_load_lds_dwordx4 v[166:167], off
	s_add_i32 m0, s46, 0x2000
	s_add_u32 s38, s38, 0x40080
	v_lshl_add_u64 v[166:167], v[170:171], 0, s[30:31]
	s_addc_u32 s39, s39, 0
	s_add_i32 s46, s60, s7
	global_load_lds_dwordx4 v[166:167], off
	v_lshl_add_u64 v[166:167], s[38:39], 0, v[168:169]
	s_mov_b32 m0, s46
	s_nop 0
	global_load_lds_dwordx4 v[166:167], off
	v_lshl_add_u64 v[166:167], s[38:39], 0, v[128:129]
	s_add_i32 m0, s46, 0x2000
	s_nop 0
	global_load_lds_dwordx4 v[166:167], off
	v_lshl_add_u64 v[166:167], v[172:173], 0, s[30:31]
	s_mov_b32 m0, s49
	s_nop 0
	global_load_lds_dwordx4 v[166:167], off
	v_lshl_add_u64 v[166:167], v[224:225], 0, s[30:31]
	s_mov_b32 m0, s50
	s_nop 0
	global_load_lds_dwordx4 v[166:167], off
	s_waitcnt vmcnt(8)
	s_waitcnt lgkmcnt(0)
	s_barrier
	s_setprio 1
	s_waitcnt lgkmcnt(0)
	v_mfma_f32_16x16x32_bf16 v[60:63], v[138:141], v[196:199], v[60:63]
	v_mfma_f32_16x16x32_bf16 v[56:59], v[150:153], v[196:199], v[56:59]
	v_mfma_f32_16x16x32_bf16 v[44:47], v[138:141], v[204:207], v[44:47]
	v_mfma_f32_16x16x32_bf16 v[40:43], v[150:153], v[204:207], v[40:43]
	v_mfma_f32_16x16x32_bf16 v[28:31], v[138:141], v[212:215], v[28:31]
	v_mfma_f32_16x16x32_bf16 v[24:27], v[150:153], v[212:215], v[24:27]
	v_mfma_f32_16x16x32_bf16 v[12:15], v[138:141], v[220:223], v[12:15]
	v_mfma_f32_16x16x32_bf16 v[8:11], v[150:153], v[220:223], v[8:11]
	v_mfma_f32_16x16x32_bf16 v[60:63], v[146:149], v[200:203], v[60:63]
	v_mfma_f32_16x16x32_bf16 v[56:59], v[154:157], v[200:203], v[56:59]
	v_mfma_f32_16x16x32_bf16 v[44:47], v[146:149], v[208:211], v[44:47]
	v_mfma_f32_16x16x32_bf16 v[40:43], v[154:157], v[208:211], v[40:43]
	v_mfma_f32_16x16x32_bf16 v[28:31], v[146:149], v[216:219], v[28:31]
	v_mfma_f32_16x16x32_bf16 v[24:27], v[154:157], v[216:219], v[24:27]
	v_mfma_f32_16x16x32_bf16 v[12:15], v[146:149], v[234:237], v[12:15]
	v_mfma_f32_16x16x32_bf16 v[8:11], v[154:157], v[234:237], v[8:11]
	s_setprio 0
	s_setprio 1
	v_mfma_f32_16x16x32_bf16 v[52:55], v[158:161], v[196:199], v[52:55]
	v_mfma_f32_16x16x32_bf16 v[48:51], v[188:191], v[196:199], v[48:51]
	v_mfma_f32_16x16x32_bf16 v[36:39], v[158:161], v[204:207], v[36:39]
	v_mfma_f32_16x16x32_bf16 v[32:35], v[188:191], v[204:207], v[32:35]
	v_mfma_f32_16x16x32_bf16 v[20:23], v[158:161], v[212:215], v[20:23]
	v_mfma_f32_16x16x32_bf16 v[16:19], v[188:191], v[212:215], v[16:19]
	v_mfma_f32_16x16x32_bf16 v[4:7], v[158:161], v[220:223], v[4:7]
	v_mfma_f32_16x16x32_bf16 v[0:3], v[188:191], v[220:223], v[0:3]
	v_mfma_f32_16x16x32_bf16 v[52:55], v[162:165], v[200:203], v[52:55]
	v_mfma_f32_16x16x32_bf16 v[48:51], v[192:195], v[200:203], v[48:51]
	v_mfma_f32_16x16x32_bf16 v[36:39], v[162:165], v[208:211], v[36:39]
	v_mfma_f32_16x16x32_bf16 v[32:35], v[192:195], v[208:211], v[32:35]
	v_mfma_f32_16x16x32_bf16 v[20:23], v[162:165], v[216:219], v[20:23]
	v_mfma_f32_16x16x32_bf16 v[16:19], v[192:195], v[216:219], v[16:19]
	v_mfma_f32_16x16x32_bf16 v[4:7], v[162:165], v[234:237], v[4:7]
	v_mfma_f32_16x16x32_bf16 v[0:3], v[192:195], v[234:237], v[0:3]
	s_setprio 0
	s_barrier
	s_add_i32 s58, s58, 2
	s_add_u32 s56, s56, 0x100
	s_addc_u32 s57, s57, 0
	s_add_u32 s4, s4, 0x100
	s_addc_u32 s5, s5, 0

; #define PG8_STAGE(bufoff, gbase, voff) do { _Pragma("unroll") for (int _i = 0; _i < 2; ++_i) \
;         __builtin_amdgcn_global_load_lds((const unsigned*)((const char*)(gbase) + (voff)[_i]), (PG8_LAS unsigned*)(lds + (bufoff) + ldsw + _i * 8192), 16, 0, 0); } while (0)
; #define PG8_LDA(dst, b, h) do { _Pragma("unroll") for (int m = 0; m < 4; ++m) _Pragma("unroll") for (int k = 0; k < 2; ++k) dst[m][k] = *(const PG8_LAS bf16x8*)(lds + PG8_SA(b, h) + aoff + m * 2048 + k * 1024); } while (0)
; template <class Epi, class Sched, bool ALIGN_EPI = false, bool SP2 = false>
; __device__ __forceinline__ void gemm_phase(PG8_LAS unsigned char* lds, const Gemm g, const Sched& S, const Epi& E) {
;     ...
;         const bool has_next = S.next(ui + 1, nxt);
;         const char* nA = has_next ? (const char*)g.A + (size_t)nxt.pm * tstepA : cA; const char* nB = has_next ? (const char*)g.Bt + (size_t)nxt.pn * tstep : cB;
;         for (int t = 0; t < nt; t += 2) {
;             const bool last = (t == nt - 2);
;             const char* a1 = cA + (size_t)(t + 1) * kstepA;
;             const char* a2 = last ? nA : cA + (size_t)(t + 2) * kstepA; const char* b2 = last ? nB : cB + (size_t)(t + 2) * kstep;
;             const char* a3 = a2 + kstepA; const char* b3 = b2 + kstep;
;             if (last && has_next) S.a_ready(nxt);
;             if constexpr (SP2) {
;             PG8_LDB(B0, 0, 0); PG8_LDB(B1, 0, 1); PG8_SCHED; PG8_LDA(At, 0, 0); PG8_STAGE(PG8_SA(1, 1), a1 + hstepA, voffA);
;             PG8_WAIT_V(8); PG8_WAIT_L(0); PG8_BAR; PG8_MMA(0, 0, At, B0); PG8_MMA(0, 1, At, B1); PG8_BAR; PG8_SCHED;
;             PG8_LDA(At, 0, 1); PG8_STAGE(PG8_SB(0, 0), b2, voffB); PG8_STAGE(PG8_SB(0, 1), b2 + hstep, voffB); PG8_STAGE(PG8_SA(0, 0), a2, voffA);
;             PG8_WAIT_V(8); PG8_WAIT_L(0); PG8_BAR; PG8_MMA(1, 0, At, B0); PG8_MMA(1, 1, At, B1); PG8_BAR; PG8_SCHED;
;             PG8_LDB(B0, 1, 0); PG8_LDB(B1, 1, 1); PG8_SCHED; PG8_LDA(At, 1, 0); PG8_STAGE(PG8_SA(0, 1), a2 + hstepA, voffA);
;             PG8_WAIT_V(8); PG8_WAIT_L(0); PG8_BAR; PG8_MMA(0, 0, At, B0); PG8_MMA(0, 1, At, B1); PG8_BAR; PG8_SCHED;
;             PG8_LDA(At, 1, 1); PG8_STAGE(PG8_SB(1, 0), b3, voffB); PG8_STAGE(PG8_SB(1, 1), b3 + hstep, voffB); PG8_STAGE(PG8_SA(1, 0), a3, voffA);
;             PG8_WAIT_V(8); PG8_WAIT_L(0); PG8_BAR; PG8_MMA(1, 0, At, B0); PG8_MMA(1, 1, At, B1); PG8_BAR; PG8_SCHED;
.LBB0_732:
	s_ashr_i32 s53, s52, 31
	s_lshl_b64 s[6:7], s[52:53], 19
	s_add_u32 s54, s78, s6
	s_addc_u32 s55, s79, s7
	s_and_b64 s[6:7], s[38:39], exec
	s_cselect_b32 s5, s55, s37
	s_cselect_b32 s6, s54, s36
	s_ashr_i32 s51, s50, 31
	s_lshl_b64 s[56:57], s[50:51], 19
	s_add_u32 s56, s2, s56
	s_addc_u32 s57, s3, s57
	s_and_b64 s[60:61], s[38:39], exec
	s_cselect_b32 s7, s57, s41
	s_cselect_b32 s51, s56, s40
	s_add_u32 s53, s40, 0x100
	s_addc_u32 s64, s41, 0
	s_add_u32 s40, s36, 0x40080
	s_addc_u32 s41, s37, 0
	s_mov_b32 s65, -2
	s_add_u32 s58, s40, 0xfffc0080
	s_addc_u32 s59, s41, -1
	s_add_i32 s74, 0, 0x10000
	s_cmp_eq_u32 s65, 12
	s_cselect_b32 s61, s5, s59
	s_cselect_b32 s60, s6, s58
	s_cselect_b32 s59, s7, s64
	s_cselect_b32 s58, s51, s53
	s_add_i32 s91, 0, 0x14000
	v_add_u32_e32 v140, s74, v224
	v_add_u32_e32 v156, s91, v224
	ds_read_b128 v[128:131], v140
	ds_read_b128 v[132:135], v140 offset:1024
	ds_read_b128 v[136:139], v140 offset:2048
	ds_read_b128 v[140:143], v140 offset:3072
	ds_read_b128 v[144:147], v156
	ds_read_b128 v[148:151], v156 offset:1024
	ds_read_b128 v[152:155], v156 offset:2048
	ds_read_b128 v[156:159], v156 offset:3072
	v_lshl_add_u64 v[178:179], s[40:41], 0, v[196:197]
	s_add_i32 m0, s35, 0xc000
	ds_read_b128 v[160:163], v225
	ds_read_b128 v[164:167], v225 offset:1024
	ds_read_b128 v[170:173], v225 offset:2048
	ds_read_b128 v[198:201], v225 offset:3072
	ds_read_b128 v[202:205], v225 offset:4096
	ds_read_b128 v[206:209], v225 offset:5120
	ds_read_b128 v[210:213], v225 offset:6144
	ds_read_b128 v[214:217], v225 offset:7168
	global_load_lds_dwordx4 v[178:179], off
	v_lshl_add_u64 v[178:179], s[40:41], 0, v[194:195]
	s_add_i32 m0, s35, 0xe000
	s_nop 0
	global_load_lds_dwordx4 v[178:179], off
	s_waitcnt vmcnt(8)
	s_waitcnt lgkmcnt(0)
	s_barrier
	s_setprio 1
	s_waitcnt lgkmcnt(0)
	v_mfma_f32_16x16x32_bf16 v[124:127], v[128:131], v[160:163], 0
	v_mfma_f32_16x16x32_bf16 v[120:123], v[136:139], v[160:163], 0
	v_mfma_f32_16x16x32_bf16 v[108:111], v[128:131], v[170:173], 0
	v_mfma_f32_16x16x32_bf16 v[104:107], v[136:139], v[170:173], 0
	v_mfma_f32_16x16x32_bf16 v[92:95], v[128:131], v[202:205], 0
	v_mfma_f32_16x16x32_bf16 v[88:91], v[136:139], v[202:205], 0
	v_mfma_f32_16x16x32_bf16 v[76:79], v[128:131], v[210:213], 0
	v_mfma_f32_16x16x32_bf16 v[72:75], v[136:139], v[210:213], 0
	v_mfma_f32_16x16x32_bf16 v[124:127], v[132:135], v[164:167], v[124:127]
	v_mfma_f32_16x16x32_bf16 v[120:123], v[140:143], v[164:167], v[120:123]
	v_mfma_f32_16x16x32_bf16 v[108:111], v[132:135], v[198:201], v[108:111]
	v_mfma_f32_16x16x32_bf16 v[104:107], v[140:143], v[198:201], v[104:107]
	v_mfma_f32_16x16x32_bf16 v[92:95], v[132:135], v[206:209], v[92:95]
	v_mfma_f32_16x16x32_bf16 v[88:91], v[140:143], v[206:209], v[88:91]
	v_mfma_f32_16x16x32_bf16 v[76:79], v[132:135], v[214:217], v[76:79]
	v_mfma_f32_16x16x32_bf16 v[72:75], v[140:143], v[214:217], v[72:75]
	s_setprio 0
	s_setprio 1
	v_mfma_f32_16x16x32_bf16 v[116:119], v[144:147], v[160:163], 0
	v_mfma_f32_16x16x32_bf16 v[112:115], v[152:155], v[160:163], 0
	v_mfma_f32_16x16x32_bf16 v[100:103], v[144:147], v[170:173], 0
	v_mfma_f32_16x16x32_bf16 v[96:99], v[152:155], v[170:173], 0
	v_mfma_f32_16x16x32_bf16 v[84:87], v[144:147], v[202:205], 0
	v_mfma_f32_16x16x32_bf16 v[80:83], v[152:155], v[202:205], 0
	v_mfma_f32_16x16x32_bf16 v[68:71], v[144:147], v[210:213], 0
	v_mfma_f32_16x16x32_bf16 v[64:67], v[152:155], v[210:213], 0
	v_mfma_f32_16x16x32_bf16 v[116:119], v[148:151], v[164:167], v[116:119]
	v_mfma_f32_16x16x32_bf16 v[112:115], v[156:159], v[164:167], v[112:115]
	v_mfma_f32_16x16x32_bf16 v[100:103], v[148:151], v[198:201], v[100:103]
	v_mfma_f32_16x16x32_bf16 v[96:99], v[156:159], v[198:201], v[96:99]
	v_mfma_f32_16x16x32_bf16 v[84:87], v[148:151], v[206:209], v[84:87]
	v_mfma_f32_16x16x32_bf16 v[80:83], v[156:159], v[206:209], v[80:83]
	v_mfma_f32_16x16x32_bf16 v[68:71], v[148:151], v[214:217], v[68:71]
	v_mfma_f32_16x16x32_bf16 v[64:67], v[156:159], v[214:217], v[64:67]
	s_setprio 0
	s_barrier
	s_add_i32 s74, s74, s34
	v_lshl_add_u64 v[178:179], s[58:59], 0, v[168:169]
	s_mov_b32 m0, s74
	ds_read_b128 v[160:163], v225 offset:16384
	ds_read_b128 v[164:167], v225 offset:17408
	ds_read_b128 v[170:173], v225 offset:18432
	ds_read_b128 v[198:201], v225 offset:19456
	ds_read_b128 v[202:205], v225 offset:20480
	ds_read_b128 v[206:209], v225 offset:21504
	ds_read_b128 v[210:213], v225 offset:22528
	ds_read_b128 v[214:217], v225 offset:23552
	global_load_lds_dwordx4 v[178:179], off
	s_add_i32 m0, s74, 0x2000
	s_add_u32 s74, s58, 0x40000
	v_lshl_add_u64 v[218:219], s[58:59], 0, v[188:189]
	s_addc_u32 s75, s59, 0
	s_add_i32 s91, s91, s34
	global_load_lds_dwordx4 v[218:219], off
	v_lshl_add_u64 v[220:221], s[74:75], 0, v[168:169]
	s_mov_b32 m0, s91
	v_lshl_add_u64 v[234:235], s[60:61], 0, v[190:191]
	global_load_lds_dwordx4 v[220:221], off
	v_lshl_add_u64 v[220:221], s[74:75], 0, v[188:189]
	s_add_i32 m0, s91, 0x2000
	s_nop 0
	global_load_lds_dwordx4 v[220:221], off
	v_lshl_add_u64 v[220:221], s[60:61], 0, v[192:193]
	s_mov_b32 m0, s35
	s_nop 0
	global_load_lds_dwordx4 v[220:221], off
	s_mov_b32 m0, s69
	s_nop 0
	global_load_lds_dwordx4 v[234:235], off
	s_waitcnt vmcnt(8)
	s_waitcnt lgkmcnt(0)
	s_barrier
; #define PG8_STAGE(bufoff, gbase, voff) do { _Pragma("unroll") for (int _i = 0; _i < 2; ++_i) \
;         __builtin_amdgcn_global_load_lds((const unsigned*)((const char*)(gbase) + (voff)[_i]), (PG8_LAS unsigned*)(lds + (bufoff) + ldsw + _i * 8192), 16, 0, 0); } while (0)
; #define PG8_LDA(dst, b, h) do { _Pragma("unroll") for (int m = 0; m < 4; ++m) _Pragma("unroll") for (int k = 0; k < 2; ++k) dst[m][k] = *(const PG8_LAS bf16x8*)(lds + PG8_SA(b, h) + aoff + m * 2048 + k * 1024); } while (0)
; #define PG8_LDB(dst, b, h) do { _Pragma("unroll") for (int n = 0; n < 2; ++n) _Pragma("unroll") for (int k = 0; k < 2; ++k) dst[n][k] = *(const PG8_LAS bf16x8*)(lds + PG8_SB(b, h) + boff + n * 2048 + k * 1024); } while (0)
; #define PG8_MMA(ai, bj, At, Bt) do { __builtin_amdgcn_s_setprio(1); _Pragma("unroll") for (int m = 0; m < 4; ++m) _Pragma("unroll") for (int n = 0; n < 2; ++n) _Pragma("unroll") for (int k = 0; k < 2; ++k) \
;         acc[ai][bj][m][n] = __builtin_amdgcn_mfma_f32_16x16x32_bf16(Bt[n][k], At[m][k], acc[ai][bj][m][n], 0, 0, 0); __builtin_amdgcn_s_setprio(0); } while (0)
; #define PG8_WAIT_V(n) asm volatile("s_waitcnt vmcnt(" #n ")" ::: "memory")
; template <class Epi, class Sched, bool ALIGN_EPI = false, bool SP2 = false>
; __device__ __forceinline__ void gemm_phase(PG8_LAS unsigned char* lds, const Gemm g, const Sched& S, const Epi& E) {
;     ...
;             PG8_LDB(B0, 0, 0); PG8_LDB(B1, 0, 1); PG8_SCHED; PG8_LDA(At, 0, 0); PG8_STAGE(PG8_SA(1, 1), a1 + hstepA, voffA);
;             PG8_WAIT_V(8); PG8_WAIT_L(0); PG8_BAR; PG8_MMA(0, 0, At, B0); PG8_MMA(0, 1, At, B1); PG8_BAR; PG8_SCHED;
;             PG8_LDA(At, 0, 1); PG8_STAGE(PG8_SB(0, 0), b2, voffB); PG8_STAGE(PG8_SB(0, 1), b2 + hstep, voffB); PG8_STAGE(PG8_SA(0, 0), a2, voffA);
;             PG8_WAIT_V(8); PG8_WAIT_L(0); PG8_BAR; PG8_MMA(1, 0, At, B0); PG8_MMA(1, 1, At, B1); PG8_BAR; PG8_SCHED;
;             PG8_LDB(B0, 1, 0); PG8_LDB(B1, 1, 1); PG8_SCHED; PG8_LDA(At, 1, 0); PG8_STAGE(PG8_SA(0, 1), a2 + hstepA, voffA);
;             PG8_WAIT_V(8); PG8_WAIT_L(0); PG8_BAR; PG8_MMA(0, 0, At, B0); PG8_MMA(0, 1, At, B1); PG8_BAR; PG8_SCHED;
;             PG8_LDA(At, 1, 1); PG8_STAGE(PG8_SB(1, 0), b3, voffB); PG8_STAGE(PG8_SB(1, 1), b3 + hstep, voffB); PG8_STAGE(PG8_SA(1, 0), a3, voffA);
;             PG8_WAIT_V(8); PG8_WAIT_L(0); PG8_BAR; PG8_MMA(1, 0, At, B0); PG8_MMA(1, 1, At, B1); PG8_BAR; PG8_SCHED;
	s_setprio 1
	s_waitcnt lgkmcnt(0)
	v_mfma_f32_16x16x32_bf16 v[60:63], v[128:131], v[160:163], 0
	v_mfma_f32_16x16x32_bf16 v[56:59], v[136:139], v[160:163], 0
	v_mfma_f32_16x16x32_bf16 v[44:47], v[128:131], v[170:173], 0
	v_mfma_f32_16x16x32_bf16 v[40:43], v[136:139], v[170:173], 0
	v_mfma_f32_16x16x32_bf16 v[28:31], v[128:131], v[202:205], 0
	v_mfma_f32_16x16x32_bf16 v[24:27], v[136:139], v[202:205], 0
	v_mfma_f32_16x16x32_bf16 v[12:15], v[128:131], v[210:213], 0
	v_mfma_f32_16x16x32_bf16 v[8:11], v[136:139], v[210:213], 0
	v_mfma_f32_16x16x32_bf16 v[60:63], v[132:135], v[164:167], v[60:63]
	v_mfma_f32_16x16x32_bf16 v[56:59], v[140:143], v[164:167], v[56:59]
	v_mfma_f32_16x16x32_bf16 v[44:47], v[132:135], v[198:201], v[44:47]
	v_mfma_f32_16x16x32_bf16 v[40:43], v[140:143], v[198:201], v[40:43]
	v_mfma_f32_16x16x32_bf16 v[28:31], v[132:135], v[206:209], v[28:31]
	v_mfma_f32_16x16x32_bf16 v[24:27], v[140:143], v[206:209], v[24:27]
	v_mfma_f32_16x16x32_bf16 v[12:15], v[132:135], v[214:217], v[12:15]
	v_mfma_f32_16x16x32_bf16 v[8:11], v[140:143], v[214:217], v[8:11]
	s_setprio 0
	s_setprio 1
	v_mfma_f32_16x16x32_bf16 v[52:55], v[144:147], v[160:163], 0
	v_mfma_f32_16x16x32_bf16 v[48:51], v[152:155], v[160:163], 0
	v_mfma_f32_16x16x32_bf16 v[36:39], v[144:147], v[170:173], 0
	v_mfma_f32_16x16x32_bf16 v[32:35], v[152:155], v[170:173], 0
	v_mfma_f32_16x16x32_bf16 v[20:23], v[144:147], v[202:205], 0
	v_mfma_f32_16x16x32_bf16 v[16:19], v[152:155], v[202:205], 0
	v_mfma_f32_16x16x32_bf16 v[4:7], v[144:147], v[210:213], 0
	v_mfma_f32_16x16x32_bf16 v[0:3], v[152:155], v[210:213], 0
	v_mfma_f32_16x16x32_bf16 v[52:55], v[148:151], v[164:167], v[52:55]
	v_mfma_f32_16x16x32_bf16 v[48:51], v[156:159], v[164:167], v[48:51]
	v_mfma_f32_16x16x32_bf16 v[36:39], v[148:151], v[198:201], v[36:39]
	v_mfma_f32_16x16x32_bf16 v[32:35], v[156:159], v[198:201], v[32:35]
	v_mfma_f32_16x16x32_bf16 v[20:23], v[148:151], v[206:209], v[20:23]
	v_mfma_f32_16x16x32_bf16 v[16:19], v[156:159], v[206:209], v[16:19]
	v_mfma_f32_16x16x32_bf16 v[4:7], v[148:151], v[214:217], v[4:7]
	v_mfma_f32_16x16x32_bf16 v[0:3], v[156:159], v[214:217], v[0:3]
	s_setprio 0
	s_barrier
	s_add_i32 s74, 0, 0x18000
	s_add_i32 s75, 0, 0x1c000
	v_add_u32_e32 v140, s74, v224
	v_add_u32_e32 v156, s75, v224
	ds_read_b128 v[128:131], v140
	ds_read_b128 v[132:135], v140 offset:1024
	ds_read_b128 v[136:139], v140 offset:2048
	ds_read_b128 v[140:143], v140 offset:3072
	ds_read_b128 v[144:147], v156
	ds_read_b128 v[148:151], v156 offset:1024
	ds_read_b128 v[152:155], v156 offset:2048
	ds_read_b128 v[156:159], v156 offset:3072
	s_add_u32 s60, s60, 0x40000
	s_addc_u32 s61, s61, 0
	s_mov_b32 m0, s73
	v_lshl_add_u64 v[236:237], s[60:61], 0, v[192:193]
	ds_read_b128 v[160:163], v225 offset:32768
	ds_read_b128 v[164:167], v225 offset:33792
	ds_read_b128 v[170:173], v225 offset:34816
	ds_read_b128 v[198:201], v225 offset:35840
	ds_read_b128 v[202:205], v225 offset:36864
	ds_read_b128 v[206:209], v225 offset:37888
	ds_read_b128 v[210:213], v225 offset:38912
	ds_read_b128 v[214:217], v225 offset:39936
	global_load_lds_dwordx4 v[236:237], off
	v_lshl_add_u64 v[236:237], s[60:61], 0, v[190:191]
	s_mov_b32 m0, s80
	s_nop 0
	global_load_lds_dwordx4 v[236:237], off
	s_waitcnt vmcnt(8)
	s_waitcnt lgkmcnt(0)
	s_barrier
	s_setprio 1
	s_waitcnt lgkmcnt(0)
	v_mfma_f32_16x16x32_bf16 v[124:127], v[128:131], v[160:163], v[124:127]
	v_mfma_f32_16x16x32_bf16 v[120:123], v[136:139], v[160:163], v[120:123]
	v_mfma_f32_16x16x32_bf16 v[108:111], v[128:131], v[170:173], v[108:111]
	v_mfma_f32_16x16x32_bf16 v[104:107], v[136:139], v[170:173], v[104:107]
	v_mfma_f32_16x16x32_bf16 v[92:95], v[128:131], v[202:205], v[92:95]
	v_mfma_f32_16x16x32_bf16 v[88:91], v[136:139], v[202:205], v[88:91]
	v_mfma_f32_16x16x32_bf16 v[76:79], v[128:131], v[210:213], v[76:79]
	v_mfma_f32_16x16x32_bf16 v[72:75], v[136:139], v[210:213], v[72:75]
	v_mfma_f32_16x16x32_bf16 v[124:127], v[132:135], v[164:167], v[124:127]
	v_mfma_f32_16x16x32_bf16 v[120:123], v[140:143], v[164:167], v[120:123]
	v_mfma_f32_16x16x32_bf16 v[108:111], v[132:135], v[198:201], v[108:111]
	v_mfma_f32_16x16x32_bf16 v[104:107], v[140:143], v[198:201], v[104:107]
	v_mfma_f32_16x16x32_bf16 v[92:95], v[132:135], v[206:209], v[92:95]
	v_mfma_f32_16x16x32_bf16 v[88:91], v[140:143], v[206:209], v[88:91]
	v_mfma_f32_16x16x32_bf16 v[76:79], v[132:135], v[214:217], v[76:79]
	v_mfma_f32_16x16x32_bf16 v[72:75], v[140:143], v[214:217], v[72:75]
	s_setprio 0
	s_setprio 1
	v_mfma_f32_16x16x32_bf16 v[116:119], v[144:147], v[160:163], v[116:119]
	v_mfma_f32_16x16x32_bf16 v[112:115], v[152:155], v[160:163], v[112:115]
	v_mfma_f32_16x16x32_bf16 v[100:103], v[144:147], v[170:173], v[100:103]
	v_mfma_f32_16x16x32_bf16 v[96:99], v[152:155], v[170:173], v[96:99]
	v_mfma_f32_16x16x32_bf16 v[84:87], v[144:147], v[202:205], v[84:87]
	v_mfma_f32_16x16x32_bf16 v[80:83], v[152:155], v[202:205], v[80:83]
	v_mfma_f32_16x16x32_bf16 v[68:71], v[144:147], v[210:213], v[68:71]
	v_mfma_f32_16x16x32_bf16 v[64:67], v[152:155], v[210:213], v[64:67]
	v_mfma_f32_16x16x32_bf16 v[116:119], v[148:151], v[164:167], v[116:119]
	v_mfma_f32_16x16x32_bf16 v[112:115], v[156:159], v[164:167], v[112:115]
	v_mfma_f32_16x16x32_bf16 v[100:103], v[148:151], v[198:201], v[100:103]
	v_mfma_f32_16x16x32_bf16 v[96:99], v[156:159], v[198:201], v[96:99]
	v_mfma_f32_16x16x32_bf16 v[84:87], v[148:151], v[206:209], v[84:87]
	v_mfma_f32_16x16x32_bf16 v[80:83], v[156:159], v[206:209], v[80:83]
	v_mfma_f32_16x16x32_bf16 v[68:71], v[148:151], v[214:217], v[68:71]
	v_mfma_f32_16x16x32_bf16 v[64:67], v[156:159], v[214:217], v[64:67]
	s_setprio 0
	s_barrier
; #define PG8_STAGE(bufoff, gbase, voff) do { _Pragma("unroll") for (int _i = 0; _i < 2; ++_i) \
;         __builtin_amdgcn_global_load_lds((const unsigned*)((const char*)(gbase) + (voff)[_i]), (PG8_LAS unsigned*)(lds + (bufoff) + ldsw + _i * 8192), 16, 0, 0); } while (0)
; #define PG8_LDA(dst, b, h) do { _Pragma("unroll") for (int m = 0; m < 4; ++m) _Pragma("unroll") for (int k = 0; k < 2; ++k) dst[m][k] = *(const PG8_LAS bf16x8*)(lds + PG8_SA(b, h) + aoff + m * 2048 + k * 1024); } while (0)
; #define PG8_LDB(dst, b, h) do { _Pragma("unroll") for (int n = 0; n < 2; ++n) _Pragma("unroll") for (int k = 0; k < 2; ++k) dst[n][k] = *(const PG8_LAS bf16x8*)(lds + PG8_SB(b, h) + boff + n * 2048 + k * 1024); } while (0)
; #define PG8_MMA(ai, bj, At, Bt) do { __builtin_amdgcn_s_setprio(1); _Pragma("unroll") for (int m = 0; m < 4; ++m) _Pragma("unroll") for (int n = 0; n < 2; ++n) _Pragma("unroll") for (int k = 0; k < 2; ++k) \
;         acc[ai][bj][m][n] = __builtin_amdgcn_mfma_f32_16x16x32_bf16(Bt[n][k], At[m][k], acc[ai][bj][m][n], 0, 0, 0); __builtin_amdgcn_s_setprio(0); } while (0)
; #define PG8_WAIT_V(n) asm volatile("s_waitcnt vmcnt(" #n ")" ::: "memory")
; #define PG8_WAIT_L(n) asm volatile("s_waitcnt lgkmcnt(" #n ")" ::: "memory")
; #define PG8_BAR __builtin_amdgcn_s_barrier()
; #define PG8_SCHED __builtin_amdgcn_sched_barrier(0)
; template <class Epi, class Sched, bool ALIGN_EPI = false, bool SP2 = false>
; __device__ __forceinline__ void gemm_phase(PG8_LAS unsigned char* lds, const Gemm g, const Sched& S, const Epi& E) {
;     ...
;             PG8_LDB(B0, 1, 0); PG8_LDB(B1, 1, 1); PG8_SCHED; PG8_LDA(At, 1, 0); PG8_STAGE(PG8_SA(0, 1), a2 + hstepA, voffA);
;             PG8_WAIT_V(8); PG8_WAIT_L(0); PG8_BAR; PG8_MMA(0, 0, At, B0); PG8_MMA(0, 1, At, B1); PG8_BAR; PG8_SCHED;
;             PG8_LDA(At, 1, 1); PG8_STAGE(PG8_SB(1, 0), b3, voffB); PG8_STAGE(PG8_SB(1, 1), b3 + hstep, voffB); PG8_STAGE(PG8_SA(1, 0), a3, voffA);
;             PG8_WAIT_V(8); PG8_WAIT_L(0); PG8_BAR; PG8_MMA(1, 0, At, B0); PG8_MMA(1, 1, At, B1); PG8_BAR; PG8_SCHED;
	s_add_i32 s60, s74, s34
	v_lshl_add_u64 v[178:179], v[178:179], 0, s[30:31]
	s_mov_b32 m0, s60
	ds_read_b128 v[160:163], v225 offset:49152
	ds_read_b128 v[164:167], v225 offset:50176
	ds_read_b128 v[170:173], v225 offset:51200
	ds_read_b128 v[198:201], v225 offset:52224
	ds_read_b128 v[202:205], v225 offset:53248
	ds_read_b128 v[206:209], v225 offset:54272
	ds_read_b128 v[210:213], v225 offset:55296
	ds_read_b128 v[214:217], v225 offset:56320
	global_load_lds_dwordx4 v[178:179], off
	s_add_i32 m0, s60, 0x2000
	s_add_u32 s58, s58, 0x40080
	v_lshl_add_u64 v[178:179], v[218:219], 0, s[30:31]
	s_addc_u32 s59, s59, 0
	s_add_i32 s60, s75, s34
	global_load_lds_dwordx4 v[178:179], off
	v_lshl_add_u64 v[178:179], s[58:59], 0, v[168:169]
	s_mov_b32 m0, s60
	s_nop 0
	global_load_lds_dwordx4 v[178:179], off
	v_lshl_add_u64 v[178:179], s[58:59], 0, v[188:189]
	s_add_i32 m0, s60, 0x2000
	s_nop 0
	global_load_lds_dwordx4 v[178:179], off
	v_lshl_add_u64 v[178:179], v[220:221], 0, s[30:31]
	s_mov_b32 m0, s84
	s_nop 0
	global_load_lds_dwordx4 v[178:179], off
	v_lshl_add_u64 v[178:179], v[234:235], 0, s[30:31]
	s_mov_b32 m0, s85
	s_nop 0
	global_load_lds_dwordx4 v[178:179], off
	s_waitcnt vmcnt(8)
	s_waitcnt lgkmcnt(0)
	s_barrier
	s_setprio 1
	s_waitcnt lgkmcnt(0)
	v_mfma_f32_16x16x32_bf16 v[60:63], v[128:131], v[160:163], v[60:63]
	v_mfma_f32_16x16x32_bf16 v[56:59], v[136:139], v[160:163], v[56:59]
	v_mfma_f32_16x16x32_bf16 v[44:47], v[128:131], v[170:173], v[44:47]
	v_mfma_f32_16x16x32_bf16 v[40:43], v[136:139], v[170:173], v[40:43]
	v_mfma_f32_16x16x32_bf16 v[28:31], v[128:131], v[202:205], v[28:31]
	v_mfma_f32_16x16x32_bf16 v[24:27], v[136:139], v[202:205], v[24:27]
	v_mfma_f32_16x16x32_bf16 v[12:15], v[128:131], v[210:213], v[12:15]
	v_mfma_f32_16x16x32_bf16 v[8:11], v[136:139], v[210:213], v[8:11]
	v_mfma_f32_16x16x32_bf16 v[60:63], v[132:135], v[164:167], v[60:63]
	v_mfma_f32_16x16x32_bf16 v[56:59], v[140:143], v[164:167], v[56:59]
	v_mfma_f32_16x16x32_bf16 v[44:47], v[132:135], v[198:201], v[44:47]
	v_mfma_f32_16x16x32_bf16 v[40:43], v[140:143], v[198:201], v[40:43]
	v_mfma_f32_16x16x32_bf16 v[28:31], v[132:135], v[206:209], v[28:31]
	v_mfma_f32_16x16x32_bf16 v[24:27], v[140:143], v[206:209], v[24:27]
	v_mfma_f32_16x16x32_bf16 v[12:15], v[132:135], v[214:217], v[12:15]
	v_mfma_f32_16x16x32_bf16 v[8:11], v[140:143], v[214:217], v[8:11]
	s_setprio 0
	s_setprio 1
	v_mfma_f32_16x16x32_bf16 v[52:55], v[144:147], v[160:163], v[52:55]
	v_mfma_f32_16x16x32_bf16 v[48:51], v[152:155], v[160:163], v[48:51]
	v_mfma_f32_16x16x32_bf16 v[36:39], v[144:147], v[170:173], v[36:39]
	v_mfma_f32_16x16x32_bf16 v[32:35], v[152:155], v[170:173], v[32:35]
	v_mfma_f32_16x16x32_bf16 v[20:23], v[144:147], v[202:205], v[20:23]
	v_mfma_f32_16x16x32_bf16 v[16:19], v[152:155], v[202:205], v[16:19]
	v_mfma_f32_16x16x32_bf16 v[4:7], v[144:147], v[210:213], v[4:7]
	v_mfma_f32_16x16x32_bf16 v[0:3], v[152:155], v[210:213], v[0:3]
	v_mfma_f32_16x16x32_bf16 v[52:55], v[148:151], v[164:167], v[52:55]
	v_mfma_f32_16x16x32_bf16 v[48:51], v[156:159], v[164:167], v[48:51]
	v_mfma_f32_16x16x32_bf16 v[36:39], v[148:151], v[198:201], v[36:39]
	v_mfma_f32_16x16x32_bf16 v[32:35], v[156:159], v[198:201], v[32:35]
	v_mfma_f32_16x16x32_bf16 v[20:23], v[148:151], v[206:209], v[20:23]
	v_mfma_f32_16x16x32_bf16 v[16:19], v[156:159], v[206:209], v[16:19]
	v_mfma_f32_16x16x32_bf16 v[4:7], v[148:151], v[214:217], v[4:7]
	v_mfma_f32_16x16x32_bf16 v[0:3], v[156:159], v[214:217], v[0:3]
	s_setprio 0
	s_barrier
	s_add_i32 s65, s65, 2
	s_add_u32 s53, s53, 0x100
	s_addc_u32 s64, s64, 0
	s_add_u32 s40, s40, 0x100
	s_addc_u32 s41, s41, 0

; #define PG8_STAGE(bufoff, gbase, voff) do { _Pragma("unroll") for (int _i = 0; _i < 2; ++_i) \
;         __builtin_amdgcn_global_load_lds((const unsigned*)((const char*)(gbase) + (voff)[_i]), (PG8_LAS unsigned*)(lds + (bufoff) + ldsw + _i * 8192), 16, 0, 0); } while (0)
; #define PG8_LDA(dst, b, h) do { _Pragma("unroll") for (int m = 0; m < 4; ++m) _Pragma("unroll") for (int k = 0; k < 2; ++k) dst[m][k] = *(const PG8_LAS bf16x8*)(lds + PG8_SA(b, h) + aoff + m * 2048 + k * 1024); } while (0)
; #define PG8_LDB(dst, b, h) do { _Pragma("unroll") for (int n = 0; n < 2; ++n) _Pragma("unroll") for (int k = 0; k < 2; ++k) dst[n][k] = *(const PG8_LAS bf16x8*)(lds + PG8_SB(b, h) + boff + n * 2048 + k * 1024); } while (0)
; #define PG8_WAIT_V(n) asm volatile("s_waitcnt vmcnt(" #n ")" ::: "memory")
; #define PG8_WAIT_L(n) asm volatile("s_waitcnt lgkmcnt(" #n ")" ::: "memory")
; #define PG8_BAR __builtin_amdgcn_s_barrier()
; #define PG8_SCHED __builtin_amdgcn_sched_barrier(0)
; template <class Epi, class Sched, bool ALIGN_EPI = false, bool SP2 = false>
; __device__ __forceinline__ void gemm_phase(PG8_LAS unsigned char* lds, const Gemm g, const Sched& S, const Epi& E) {
;     ...
;         const bool has_next = S.next(ui + 1, nxt);
;         const char* nA = has_next ? (const char*)g.A + (size_t)nxt.pm * tstepA : cA; const char* nB = has_next ? (const char*)g.Bt + (size_t)nxt.pn * tstep : cB;
;         for (int t = 0; t < nt; t += 2) {
;             const bool last = (t == nt - 2);
;             const char* a1 = cA + (size_t)(t + 1) * kstepA;
;             const char* a2 = last ? nA : cA + (size_t)(t + 2) * kstepA; const char* b2 = last ? nB : cB + (size_t)(t + 2) * kstep;
;             const char* a3 = a2 + kstepA; const char* b3 = b2 + kstep;
;             if (last && has_next) S.a_ready(nxt);
;             if constexpr (SP2) {
;             PG8_LDB(B0, 0, 0); PG8_LDB(B1, 0, 1); PG8_SCHED; PG8_LDA(At, 0, 0); PG8_STAGE(PG8_SA(1, 1), a1 + hstepA, voffA);
;             PG8_WAIT_V(8); PG8_WAIT_L(0); PG8_BAR; PG8_MMA(0, 0, At, B0); PG8_MMA(0, 1, At, B1); PG8_BAR; PG8_SCHED;
;             PG8_LDA(At, 0, 1); PG8_STAGE(PG8_SB(0, 0), b2, voffB); PG8_STAGE(PG8_SB(0, 1), b2 + hstep, voffB); PG8_STAGE(PG8_SA(0, 0), a2, voffA);
;             PG8_WAIT_V(8); PG8_WAIT_L(0); PG8_BAR; PG8_MMA(1, 0, At, B0); PG8_MMA(1, 1, At, B1); PG8_BAR; PG8_SCHED;
.LBB0_835:
	s_ashr_i32 s43, s42, 31
	s_lshl_b64 s[44:45], s[42:43], 19
	s_add_u32 s44, s20, s44
	s_addc_u32 s45, s21, s45
	s_and_b64 s[46:47], s[38:39], exec
	s_cselect_b32 s43, s45, s51
	s_cselect_b32 s61, s44, s50
	s_ashr_i32 s41, s40, 31
	s_lshl_b64 s[46:47], s[40:41], 19
	s_add_u32 s46, s2, s46
	s_addc_u32 s47, s3, s47
	s_and_b64 s[52:53], s[38:39], exec
	s_cselect_b32 s41, s47, s49
	s_cselect_b32 s64, s46, s48
	s_add_u32 s65, s48, 0x100
	s_addc_u32 s69, s49, 0
	s_add_u32 s48, s50, 0x40080
	s_addc_u32 s49, s51, 0
	s_mov_b32 s73, -2
	s_add_u32 s50, s48, 0xfffc0080
	s_addc_u32 s51, s49, -1
	s_add_i32 s74, 0, 0x10000
	s_cmp_eq_u32 s73, 12
	s_cselect_b32 s53, s43, s51
	s_cselect_b32 s52, s61, s50
	s_cselect_b32 s51, s41, s69
	s_cselect_b32 s50, s64, s65
	s_add_i32 s80, 0, 0x14000
	v_add_u32_e32 v156, s74, v142
	v_add_u32_e32 v178, s80, v142
	ds_read_b128 v[144:147], v156
	ds_read_b128 v[148:151], v156 offset:1024
	ds_read_b128 v[152:155], v156 offset:2048
	ds_read_b128 v[156:159], v156 offset:3072
	ds_read_b128 v[160:163], v178
	ds_read_b128 v[164:167], v178 offset:1024
	ds_read_b128 v[170:173], v178 offset:2048
	ds_read_b128 v[188:191], v178 offset:3072
	v_lshl_add_u64 v[178:179], s[48:49], 0, v[140:141]
	s_add_i32 m0, s7, 0xc000
	ds_read_b128 v[192:195], v143
	ds_read_b128 v[196:199], v143 offset:1024
	ds_read_b128 v[200:203], v143 offset:2048
	ds_read_b128 v[204:207], v143 offset:3072
	ds_read_b128 v[208:211], v143 offset:4096
	ds_read_b128 v[212:215], v143 offset:5120
	ds_read_b128 v[216:219], v143 offset:6144
	ds_read_b128 v[220:223], v143 offset:7168
	global_load_lds_dwordx4 v[178:179], off
	v_lshl_add_u64 v[178:179], s[48:49], 0, v[138:139]
	s_add_i32 m0, s7, 0xe000
	s_nop 0
	global_load_lds_dwordx4 v[178:179], off
	s_waitcnt vmcnt(8)
	s_waitcnt lgkmcnt(0)
	s_barrier
	s_setprio 1
	s_waitcnt lgkmcnt(0)
	v_mfma_f32_16x16x32_bf16 v[124:127], v[144:147], v[192:195], 0
	v_mfma_f32_16x16x32_bf16 v[116:119], v[152:155], v[192:195], 0
	v_mfma_f32_16x16x32_bf16 v[108:111], v[144:147], v[200:203], 0
	v_mfma_f32_16x16x32_bf16 v[100:103], v[152:155], v[200:203], 0
	v_mfma_f32_16x16x32_bf16 v[92:95], v[144:147], v[208:211], 0
	v_mfma_f32_16x16x32_bf16 v[84:87], v[152:155], v[208:211], 0
	v_mfma_f32_16x16x32_bf16 v[76:79], v[144:147], v[216:219], 0
	v_mfma_f32_16x16x32_bf16 v[68:71], v[152:155], v[216:219], 0
	v_mfma_f32_16x16x32_bf16 v[124:127], v[148:151], v[196:199], v[124:127]
	v_mfma_f32_16x16x32_bf16 v[116:119], v[156:159], v[196:199], v[116:119]
	v_mfma_f32_16x16x32_bf16 v[108:111], v[148:151], v[204:207], v[108:111]
	v_mfma_f32_16x16x32_bf16 v[100:103], v[156:159], v[204:207], v[100:103]
	v_mfma_f32_16x16x32_bf16 v[92:95], v[148:151], v[212:215], v[92:95]
	v_mfma_f32_16x16x32_bf16 v[84:87], v[156:159], v[212:215], v[84:87]
	v_mfma_f32_16x16x32_bf16 v[76:79], v[148:151], v[220:223], v[76:79]
	v_mfma_f32_16x16x32_bf16 v[68:71], v[156:159], v[220:223], v[68:71]
	s_setprio 0
	s_setprio 1
	v_mfma_f32_16x16x32_bf16 v[120:123], v[160:163], v[192:195], 0
	v_mfma_f32_16x16x32_bf16 v[112:115], v[170:173], v[192:195], 0
	v_mfma_f32_16x16x32_bf16 v[104:107], v[160:163], v[200:203], 0
	v_mfma_f32_16x16x32_bf16 v[96:99], v[170:173], v[200:203], 0
	v_mfma_f32_16x16x32_bf16 v[88:91], v[160:163], v[208:211], 0
	v_mfma_f32_16x16x32_bf16 v[80:83], v[170:173], v[208:211], 0
	v_mfma_f32_16x16x32_bf16 v[72:75], v[160:163], v[216:219], 0
	v_mfma_f32_16x16x32_bf16 v[64:67], v[170:173], v[216:219], 0
	v_mfma_f32_16x16x32_bf16 v[120:123], v[164:167], v[196:199], v[120:123]
	v_mfma_f32_16x16x32_bf16 v[112:115], v[188:191], v[196:199], v[112:115]
	v_mfma_f32_16x16x32_bf16 v[104:107], v[164:167], v[204:207], v[104:107]
	v_mfma_f32_16x16x32_bf16 v[96:99], v[188:191], v[204:207], v[96:99]
	v_mfma_f32_16x16x32_bf16 v[88:91], v[164:167], v[212:215], v[88:91]
	v_mfma_f32_16x16x32_bf16 v[80:83], v[188:191], v[212:215], v[80:83]
	v_mfma_f32_16x16x32_bf16 v[72:75], v[164:167], v[220:223], v[72:75]
	v_mfma_f32_16x16x32_bf16 v[64:67], v[188:191], v[220:223], v[64:67]
	s_setprio 0
	s_barrier
	s_add_i32 s74, s74, s6
	v_lshl_add_u64 v[178:179], s[50:51], 0, v[132:133]
	s_mov_b32 m0, s74
	ds_read_b128 v[192:195], v143 offset:16384
	ds_read_b128 v[196:199], v143 offset:17408
	ds_read_b128 v[200:203], v143 offset:18432
	ds_read_b128 v[204:207], v143 offset:19456
	ds_read_b128 v[208:211], v143 offset:20480
	ds_read_b128 v[212:215], v143 offset:21504
	ds_read_b128 v[216:219], v143 offset:22528
	ds_read_b128 v[220:223], v143 offset:23552
	global_load_lds_dwordx4 v[178:179], off
	s_add_i32 m0, s74, 0x2000
	s_add_u32 s74, s50, 0x40000
	v_lshl_add_u64 v[224:225], s[50:51], 0, v[128:129]
	s_addc_u32 s75, s51, 0
	s_add_i32 s80, s80, s6
	global_load_lds_dwordx4 v[224:225], off
	v_lshl_add_u64 v[234:235], s[74:75], 0, v[132:133]
	s_mov_b32 m0, s80
	v_lshl_add_u64 v[236:237], s[52:53], 0, v[130:131]
	global_load_lds_dwordx4 v[234:235], off
	v_lshl_add_u64 v[234:235], s[74:75], 0, v[128:129]
	s_add_i32 m0, s80, 0x2000
	s_nop 0
	global_load_lds_dwordx4 v[234:235], off
	v_lshl_add_u64 v[234:235], s[52:53], 0, v[134:135]
	s_mov_b32 m0, s7
	s_nop 0
	global_load_lds_dwordx4 v[234:235], off
	s_mov_b32 m0, s34
	s_nop 0
	global_load_lds_dwordx4 v[236:237], off
	s_waitcnt vmcnt(8)
	s_waitcnt lgkmcnt(0)
	s_barrier
; #define PG8_STAGE(bufoff, gbase, voff) do { _Pragma("unroll") for (int _i = 0; _i < 2; ++_i) \
;         __builtin_amdgcn_global_load_lds((const unsigned*)((const char*)(gbase) + (voff)[_i]), (PG8_LAS unsigned*)(lds + (bufoff) + ldsw + _i * 8192), 16, 0, 0); } while (0)
; #define PG8_LDA(dst, b, h) do { _Pragma("unroll") for (int m = 0; m < 4; ++m) _Pragma("unroll") for (int k = 0; k < 2; ++k) dst[m][k] = *(const PG8_LAS bf16x8*)(lds + PG8_SA(b, h) + aoff + m * 2048 + k * 1024); } while (0)
; #define PG8_LDB(dst, b, h) do { _Pragma("unroll") for (int n = 0; n < 2; ++n) _Pragma("unroll") for (int k = 0; k < 2; ++k) dst[n][k] = *(const PG8_LAS bf16x8*)(lds + PG8_SB(b, h) + boff + n * 2048 + k * 1024); } while (0)
; #define PG8_MMA(ai, bj, At, Bt) do { __builtin_amdgcn_s_setprio(1); _Pragma("unroll") for (int m = 0; m < 4; ++m) _Pragma("unroll") for (int n = 0; n < 2; ++n) _Pragma("unroll") for (int k = 0; k < 2; ++k) \
;         acc[ai][bj][m][n] = __builtin_amdgcn_mfma_f32_16x16x32_bf16(Bt[n][k], At[m][k], acc[ai][bj][m][n], 0, 0, 0); __builtin_amdgcn_s_setprio(0); } while (0)
; #define PG8_WAIT_V(n) asm volatile("s_waitcnt vmcnt(" #n ")" ::: "memory")
; #define PG8_WAIT_L(n) asm volatile("s_waitcnt lgkmcnt(" #n ")" ::: "memory")
; #define PG8_BAR __builtin_amdgcn_s_barrier()
; #define PG8_SCHED __builtin_amdgcn_sched_barrier(0)
; template <class Epi, class Sched, bool ALIGN_EPI = false, bool SP2 = false>
; __device__ __forceinline__ void gemm_phase(PG8_LAS unsigned char* lds, const Gemm g, const Sched& S, const Epi& E) {
;     ...
;             PG8_WAIT_V(8); PG8_WAIT_L(0); PG8_BAR; PG8_MMA(1, 0, At, B0); PG8_MMA(1, 1, At, B1); PG8_BAR; PG8_SCHED;
;             PG8_LDB(B0, 1, 0); PG8_LDB(B1, 1, 1); PG8_SCHED; PG8_LDA(At, 1, 0); PG8_STAGE(PG8_SA(0, 1), a2 + hstepA, voffA);
;             PG8_WAIT_V(8); PG8_WAIT_L(0); PG8_BAR; PG8_MMA(0, 0, At, B0); PG8_MMA(0, 1, At, B1); PG8_BAR; PG8_SCHED;
	s_setprio 1
	s_waitcnt lgkmcnt(0)
	v_mfma_f32_16x16x32_bf16 v[60:63], v[144:147], v[192:195], 0
	v_mfma_f32_16x16x32_bf16 v[52:55], v[152:155], v[192:195], 0
	v_mfma_f32_16x16x32_bf16 v[44:47], v[144:147], v[200:203], 0
	v_mfma_f32_16x16x32_bf16 v[36:39], v[152:155], v[200:203], 0
	v_mfma_f32_16x16x32_bf16 v[28:31], v[144:147], v[208:211], 0
	v_mfma_f32_16x16x32_bf16 v[20:23], v[152:155], v[208:211], 0
	v_mfma_f32_16x16x32_bf16 v[12:15], v[144:147], v[216:219], 0
	v_mfma_f32_16x16x32_bf16 v[4:7], v[152:155], v[216:219], 0
	v_mfma_f32_16x16x32_bf16 v[60:63], v[148:151], v[196:199], v[60:63]
	v_mfma_f32_16x16x32_bf16 v[52:55], v[156:159], v[196:199], v[52:55]
	v_mfma_f32_16x16x32_bf16 v[44:47], v[148:151], v[204:207], v[44:47]
	v_mfma_f32_16x16x32_bf16 v[36:39], v[156:159], v[204:207], v[36:39]
	v_mfma_f32_16x16x32_bf16 v[28:31], v[148:151], v[212:215], v[28:31]
	v_mfma_f32_16x16x32_bf16 v[20:23], v[156:159], v[212:215], v[20:23]
	v_mfma_f32_16x16x32_bf16 v[12:15], v[148:151], v[220:223], v[12:15]
	v_mfma_f32_16x16x32_bf16 v[4:7], v[156:159], v[220:223], v[4:7]
	s_setprio 0
	s_setprio 1
	v_mfma_f32_16x16x32_bf16 v[56:59], v[160:163], v[192:195], 0
	v_mfma_f32_16x16x32_bf16 v[48:51], v[170:173], v[192:195], 0
	v_mfma_f32_16x16x32_bf16 v[40:43], v[160:163], v[200:203], 0
	v_mfma_f32_16x16x32_bf16 v[32:35], v[170:173], v[200:203], 0
	v_mfma_f32_16x16x32_bf16 v[24:27], v[160:163], v[208:211], 0
	v_mfma_f32_16x16x32_bf16 v[16:19], v[170:173], v[208:211], 0
	v_mfma_f32_16x16x32_bf16 v[8:11], v[160:163], v[216:219], 0
	v_mfma_f32_16x16x32_bf16 v[0:3], v[170:173], v[216:219], 0
	v_mfma_f32_16x16x32_bf16 v[56:59], v[164:167], v[196:199], v[56:59]
	v_mfma_f32_16x16x32_bf16 v[48:51], v[188:191], v[196:199], v[48:51]
	v_mfma_f32_16x16x32_bf16 v[40:43], v[164:167], v[204:207], v[40:43]
	v_mfma_f32_16x16x32_bf16 v[32:35], v[188:191], v[204:207], v[32:35]
	v_mfma_f32_16x16x32_bf16 v[24:27], v[164:167], v[212:215], v[24:27]
	v_mfma_f32_16x16x32_bf16 v[16:19], v[188:191], v[212:215], v[16:19]
	v_mfma_f32_16x16x32_bf16 v[8:11], v[164:167], v[220:223], v[8:11]
	v_mfma_f32_16x16x32_bf16 v[0:3], v[188:191], v[220:223], v[0:3]
	s_setprio 0
	s_barrier
	s_add_i32 s74, 0, 0x18000
	s_add_i32 s75, 0, 0x1c000
	v_add_u32_e32 v156, s74, v142
	v_add_u32_e32 v188, s75, v142
	ds_read_b128 v[144:147], v156
	ds_read_b128 v[148:151], v156 offset:1024
	ds_read_b128 v[152:155], v156 offset:2048
	ds_read_b128 v[156:159], v156 offset:3072
	ds_read_b128 v[160:163], v188
	ds_read_b128 v[164:167], v188 offset:1024
	ds_read_b128 v[170:173], v188 offset:2048
	ds_read_b128 v[188:191], v188 offset:3072
	s_add_u32 s52, s52, 0x40000
	s_addc_u32 s53, s53, 0
	s_mov_b32 m0, s35
	v_lshl_add_u64 v[238:239], s[52:53], 0, v[134:135]
	ds_read_b128 v[192:195], v143 offset:32768
	ds_read_b128 v[196:199], v143 offset:33792
	ds_read_b128 v[200:203], v143 offset:34816
	ds_read_b128 v[204:207], v143 offset:35840
	ds_read_b128 v[208:211], v143 offset:36864
	ds_read_b128 v[212:215], v143 offset:37888
	ds_read_b128 v[216:219], v143 offset:38912
	ds_read_b128 v[220:223], v143 offset:39936
	global_load_lds_dwordx4 v[238:239], off
	v_lshl_add_u64 v[238:239], s[52:53], 0, v[130:131]
	s_mov_b32 m0, s54
	s_nop 0
	global_load_lds_dwordx4 v[238:239], off
	s_waitcnt vmcnt(8)
	s_waitcnt lgkmcnt(0)
	s_barrier
	s_setprio 1
	s_waitcnt lgkmcnt(0)
	v_mfma_f32_16x16x32_bf16 v[124:127], v[144:147], v[192:195], v[124:127]
	v_mfma_f32_16x16x32_bf16 v[116:119], v[152:155], v[192:195], v[116:119]
	v_mfma_f32_16x16x32_bf16 v[108:111], v[144:147], v[200:203], v[108:111]
	v_mfma_f32_16x16x32_bf16 v[100:103], v[152:155], v[200:203], v[100:103]
	v_mfma_f32_16x16x32_bf16 v[92:95], v[144:147], v[208:211], v[92:95]
	v_mfma_f32_16x16x32_bf16 v[84:87], v[152:155], v[208:211], v[84:87]
	v_mfma_f32_16x16x32_bf16 v[76:79], v[144:147], v[216:219], v[76:79]
	v_mfma_f32_16x16x32_bf16 v[68:71], v[152:155], v[216:219], v[68:71]
	v_mfma_f32_16x16x32_bf16 v[124:127], v[148:151], v[196:199], v[124:127]
	v_mfma_f32_16x16x32_bf16 v[116:119], v[156:159], v[196:199], v[116:119]
	v_mfma_f32_16x16x32_bf16 v[108:111], v[148:151], v[204:207], v[108:111]
	v_mfma_f32_16x16x32_bf16 v[100:103], v[156:159], v[204:207], v[100:103]
	v_mfma_f32_16x16x32_bf16 v[92:95], v[148:151], v[212:215], v[92:95]
	v_mfma_f32_16x16x32_bf16 v[84:87], v[156:159], v[212:215], v[84:87]
	v_mfma_f32_16x16x32_bf16 v[76:79], v[148:151], v[220:223], v[76:79]
	v_mfma_f32_16x16x32_bf16 v[68:71], v[156:159], v[220:223], v[68:71]
	s_setprio 0
	s_setprio 1
	v_mfma_f32_16x16x32_bf16 v[120:123], v[160:163], v[192:195], v[120:123]
	v_mfma_f32_16x16x32_bf16 v[112:115], v[170:173], v[192:195], v[112:115]
	v_mfma_f32_16x16x32_bf16 v[104:107], v[160:163], v[200:203], v[104:107]
	v_mfma_f32_16x16x32_bf16 v[96:99], v[170:173], v[200:203], v[96:99]
	v_mfma_f32_16x16x32_bf16 v[88:91], v[160:163], v[208:211], v[88:91]
	v_mfma_f32_16x16x32_bf16 v[80:83], v[170:173], v[208:211], v[80:83]
	v_mfma_f32_16x16x32_bf16 v[72:75], v[160:163], v[216:219], v[72:75]
	v_mfma_f32_16x16x32_bf16 v[64:67], v[170:173], v[216:219], v[64:67]
	v_mfma_f32_16x16x32_bf16 v[120:123], v[164:167], v[196:199], v[120:123]
	v_mfma_f32_16x16x32_bf16 v[112:115], v[188:191], v[196:199], v[112:115]
	v_mfma_f32_16x16x32_bf16 v[104:107], v[164:167], v[204:207], v[104:107]
	v_mfma_f32_16x16x32_bf16 v[96:99], v[188:191], v[204:207], v[96:99]
	v_mfma_f32_16x16x32_bf16 v[88:91], v[164:167], v[212:215], v[88:91]
	v_mfma_f32_16x16x32_bf16 v[80:83], v[188:191], v[212:215], v[80:83]
	v_mfma_f32_16x16x32_bf16 v[72:75], v[164:167], v[220:223], v[72:75]
	v_mfma_f32_16x16x32_bf16 v[64:67], v[188:191], v[220:223], v[64:67]
	s_setprio 0
	s_barrier
; #define PG8_STAGE(bufoff, gbase, voff) do { _Pragma("unroll") for (int _i = 0; _i < 2; ++_i) \
;         __builtin_amdgcn_global_load_lds((const unsigned*)((const char*)(gbase) + (voff)[_i]), (PG8_LAS unsigned*)(lds + (bufoff) + ldsw + _i * 8192), 16, 0, 0); } while (0)
; #define PG8_LDA(dst, b, h) do { _Pragma("unroll") for (int m = 0; m < 4; ++m) _Pragma("unroll") for (int k = 0; k < 2; ++k) dst[m][k] = *(const PG8_LAS bf16x8*)(lds + PG8_SA(b, h) + aoff + m * 2048 + k * 1024); } while (0)
; #define PG8_MMA(ai, bj, At, Bt) do { __builtin_amdgcn_s_setprio(1); _Pragma("unroll") for (int m = 0; m < 4; ++m) _Pragma("unroll") for (int n = 0; n < 2; ++n) _Pragma("unroll") for (int k = 0; k < 2; ++k) \
;         acc[ai][bj][m][n] = __builtin_amdgcn_mfma_f32_16x16x32_bf16(Bt[n][k], At[m][k], acc[ai][bj][m][n], 0, 0, 0); __builtin_amdgcn_s_setprio(0); } while (0)
; #define PG8_WAIT_V(n) asm volatile("s_waitcnt vmcnt(" #n ")" ::: "memory")
; #define PG8_WAIT_L(n) asm volatile("s_waitcnt lgkmcnt(" #n ")" ::: "memory")
; #define PG8_BAR __builtin_amdgcn_s_barrier()
; #define PG8_SCHED __builtin_amdgcn_sched_barrier(0)
; template <class Epi, class Sched, bool ALIGN_EPI = false, bool SP2 = false>
; __device__ __forceinline__ void gemm_phase(PG8_LAS unsigned char* lds, const Gemm g, const Sched& S, const Epi& E) {
;     ...
;         for (int t = 0; t < nt; t += 2) {
;             const bool last = (t == nt - 2);
;             const char* a1 = cA + (size_t)(t + 1) * kstepA;
;             const char* a2 = last ? nA : cA + (size_t)(t + 2) * kstepA; const char* b2 = last ? nB : cB + (size_t)(t + 2) * kstep;
;             const char* a3 = a2 + kstepA; const char* b3 = b2 + kstep;
;     ...
;             PG8_LDA(At, 1, 1); PG8_STAGE(PG8_SB(1, 0), b3, voffB); PG8_STAGE(PG8_SB(1, 1), b3 + hstep, voffB); PG8_STAGE(PG8_SA(1, 0), a3, voffA);
;             PG8_WAIT_V(8); PG8_WAIT_L(0); PG8_BAR; PG8_MMA(1, 0, At, B0); PG8_MMA(1, 1, At, B1); PG8_BAR; PG8_SCHED;
	s_add_i32 s52, s74, s6
	v_lshl_add_u64 v[178:179], v[178:179], 0, s[30:31]
	s_mov_b32 m0, s52
	ds_read_b128 v[192:195], v143 offset:49152
	ds_read_b128 v[196:199], v143 offset:50176
	ds_read_b128 v[200:203], v143 offset:51200
	ds_read_b128 v[204:207], v143 offset:52224
	ds_read_b128 v[208:211], v143 offset:53248
	ds_read_b128 v[212:215], v143 offset:54272
	ds_read_b128 v[216:219], v143 offset:55296
	ds_read_b128 v[220:223], v143 offset:56320
	global_load_lds_dwordx4 v[178:179], off
	s_add_i32 m0, s52, 0x2000
	s_add_u32 s50, s50, 0x40080
	v_lshl_add_u64 v[178:179], v[224:225], 0, s[30:31]
	s_addc_u32 s51, s51, 0
	s_add_i32 s52, s75, s6
	global_load_lds_dwordx4 v[178:179], off
	v_lshl_add_u64 v[178:179], s[50:51], 0, v[132:133]
	s_mov_b32 m0, s52
	s_nop 0
	global_load_lds_dwordx4 v[178:179], off
	v_lshl_add_u64 v[178:179], s[50:51], 0, v[128:129]
	s_add_i32 m0, s52, 0x2000
	s_nop 0
	global_load_lds_dwordx4 v[178:179], off
	v_lshl_add_u64 v[178:179], v[234:235], 0, s[30:31]
	s_mov_b32 m0, s55
	s_nop 0
	global_load_lds_dwordx4 v[178:179], off
	v_lshl_add_u64 v[178:179], v[236:237], 0, s[30:31]
	s_mov_b32 m0, s56
	s_nop 0
	global_load_lds_dwordx4 v[178:179], off
	s_waitcnt vmcnt(8)
	s_waitcnt lgkmcnt(0)
	s_barrier
	s_setprio 1
	s_waitcnt lgkmcnt(0)
	v_mfma_f32_16x16x32_bf16 v[60:63], v[144:147], v[192:195], v[60:63]
	v_mfma_f32_16x16x32_bf16 v[52:55], v[152:155], v[192:195], v[52:55]
	v_mfma_f32_16x16x32_bf16 v[44:47], v[144:147], v[200:203], v[44:47]
	v_mfma_f32_16x16x32_bf16 v[36:39], v[152:155], v[200:203], v[36:39]
	v_mfma_f32_16x16x32_bf16 v[28:31], v[144:147], v[208:211], v[28:31]
	v_mfma_f32_16x16x32_bf16 v[20:23], v[152:155], v[208:211], v[20:23]
	v_mfma_f32_16x16x32_bf16 v[12:15], v[144:147], v[216:219], v[12:15]
	v_mfma_f32_16x16x32_bf16 v[4:7], v[152:155], v[216:219], v[4:7]
	v_mfma_f32_16x16x32_bf16 v[60:63], v[148:151], v[196:199], v[60:63]
	v_mfma_f32_16x16x32_bf16 v[52:55], v[156:159], v[196:199], v[52:55]
	v_mfma_f32_16x16x32_bf16 v[44:47], v[148:151], v[204:207], v[44:47]
	v_mfma_f32_16x16x32_bf16 v[36:39], v[156:159], v[204:207], v[36:39]
	v_mfma_f32_16x16x32_bf16 v[28:31], v[148:151], v[212:215], v[28:31]
	v_mfma_f32_16x16x32_bf16 v[20:23], v[156:159], v[212:215], v[20:23]
	v_mfma_f32_16x16x32_bf16 v[12:15], v[148:151], v[220:223], v[12:15]
	v_mfma_f32_16x16x32_bf16 v[4:7], v[156:159], v[220:223], v[4:7]
	s_setprio 0
	s_setprio 1
	v_mfma_f32_16x16x32_bf16 v[56:59], v[160:163], v[192:195], v[56:59]
	v_mfma_f32_16x16x32_bf16 v[48:51], v[170:173], v[192:195], v[48:51]
	v_mfma_f32_16x16x32_bf16 v[40:43], v[160:163], v[200:203], v[40:43]
	v_mfma_f32_16x16x32_bf16 v[32:35], v[170:173], v[200:203], v[32:35]
	v_mfma_f32_16x16x32_bf16 v[24:27], v[160:163], v[208:211], v[24:27]
	v_mfma_f32_16x16x32_bf16 v[16:19], v[170:173], v[208:211], v[16:19]
	v_mfma_f32_16x16x32_bf16 v[8:11], v[160:163], v[216:219], v[8:11]
	v_mfma_f32_16x16x32_bf16 v[0:3], v[170:173], v[216:219], v[0:3]
	v_mfma_f32_16x16x32_bf16 v[56:59], v[164:167], v[196:199], v[56:59]
	v_mfma_f32_16x16x32_bf16 v[48:51], v[188:191], v[196:199], v[48:51]
	v_mfma_f32_16x16x32_bf16 v[40:43], v[164:167], v[204:207], v[40:43]
	v_mfma_f32_16x16x32_bf16 v[32:35], v[188:191], v[204:207], v[32:35]
	v_mfma_f32_16x16x32_bf16 v[24:27], v[164:167], v[212:215], v[24:27]
	v_mfma_f32_16x16x32_bf16 v[16:19], v[188:191], v[212:215], v[16:19]
	v_mfma_f32_16x16x32_bf16 v[8:11], v[164:167], v[220:223], v[8:11]
	v_mfma_f32_16x16x32_bf16 v[0:3], v[188:191], v[220:223], v[0:3]
	s_setprio 0
	s_barrier
	s_add_i32 s73, s73, 2
	s_add_u32 s65, s65, 0x100
	s_addc_u32 s69, s69, 0
	s_add_u32 s48, s48, 0x100
	s_addc_u32 s49, s49, 0

; #define PG8_STAGE(bufoff, gbase, voff) do { _Pragma("unroll") for (int _i = 0; _i < 2; ++_i) \
;         __builtin_amdgcn_global_load_lds((const unsigned*)((const char*)(gbase) + (voff)[_i]), (PG8_LAS unsigned*)(lds + (bufoff) + ldsw + _i * 8192), 16, 0, 0); } while (0)
; #define PG8_LDA(dst, b, h) do { _Pragma("unroll") for (int m = 0; m < 4; ++m) _Pragma("unroll") for (int k = 0; k < 2; ++k) dst[m][k] = *(const PG8_LAS bf16x8*)(lds + PG8_SA(b, h) + aoff + m * 2048 + k * 1024); } while (0)
; #define PG8_LDB(dst, b, h) do { _Pragma("unroll") for (int n = 0; n < 2; ++n) _Pragma("unroll") for (int k = 0; k < 2; ++k) dst[n][k] = *(const PG8_LAS bf16x8*)(lds + PG8_SB(b, h) + boff + n * 2048 + k * 1024); } while (0)
; #define PG8_WAIT_V(n) asm volatile("s_waitcnt vmcnt(" #n ")" ::: "memory")
; #define PG8_WAIT_L(n) asm volatile("s_waitcnt lgkmcnt(" #n ")" ::: "memory")
; #define PG8_BAR __builtin_amdgcn_s_barrier()
; #define PG8_SCHED __builtin_amdgcn_sched_barrier(0)
; template <class Epi, class Sched, bool ALIGN_EPI = false, bool SP2 = false>
; __device__ __forceinline__ void gemm_phase(PG8_LAS unsigned char* lds, const Gemm g, const Sched& S, const Epi& E) {
;     ...
;         const bool has_next = S.next(ui + 1, nxt);
;         const char* nA = has_next ? (const char*)g.A + (size_t)nxt.pm * tstepA : cA; const char* nB = has_next ? (const char*)g.Bt + (size_t)nxt.pn * tstep : cB;
;         for (int t = 0; t < nt; t += 2) {
;             const bool last = (t == nt - 2);
;             const char* a1 = cA + (size_t)(t + 1) * kstepA;
;             const char* a2 = last ? nA : cA + (size_t)(t + 2) * kstepA; const char* b2 = last ? nB : cB + (size_t)(t + 2) * kstep;
;             const char* a3 = a2 + kstepA; const char* b3 = b2 + kstep;
;             if (last && has_next) S.a_ready(nxt);
;             if constexpr (SP2) {
;             PG8_LDB(B0, 0, 0); PG8_LDB(B1, 0, 1); PG8_SCHED; PG8_LDA(At, 0, 0); PG8_STAGE(PG8_SA(1, 1), a1 + hstepA, voffA);
;             PG8_WAIT_V(8); PG8_WAIT_L(0); PG8_BAR; PG8_MMA(0, 0, At, B0); PG8_MMA(0, 1, At, B1); PG8_BAR; PG8_SCHED;
;             PG8_LDA(At, 0, 1); PG8_STAGE(PG8_SB(0, 0), b2, voffB); PG8_STAGE(PG8_SB(0, 1), b2 + hstep, voffB); PG8_STAGE(PG8_SA(0, 0), a2, voffA);
;             PG8_WAIT_V(8); PG8_WAIT_L(0); PG8_BAR; PG8_MMA(1, 0, At, B0); PG8_MMA(1, 1, At, B1); PG8_BAR; PG8_SCHED;
.LBB0_912:
	s_add_u32 s5, s52, 0x100
	s_addc_u32 s6, s53, 0
	s_add_u32 s40, s54, 0xb4000
	s_addc_u32 s41, s55, 0
	s_mov_b32 s7, -2
	s_add_u32 s52, s40, 0xfff54000
	s_addc_u32 s53, s41, -1
	s_cmp_eq_u32 s7, 40
	s_cselect_b32 s56, s48, s52
	s_cselect_b32 s57, s49, s53
	s_cselect_b32 s54, s50, s5
	s_cselect_b32 s55, s51, s6
	s_add_u32 s52, s56, 0x4000
	s_addc_u32 s53, s57, 0
	s_add_i32 s64, 0, 0x10000
	s_add_i32 s74, 0, 0x14000
	v_add_u32_e32 v140, s64, v224
	v_add_u32_e32 v156, s74, v224
	ds_read_b128 v[128:131], v140
	ds_read_b128 v[132:135], v140 offset:1024
	ds_read_b128 v[136:139], v140 offset:2048
	ds_read_b128 v[140:143], v140 offset:3072
	ds_read_b128 v[144:147], v156
	ds_read_b128 v[148:151], v156 offset:1024
	ds_read_b128 v[152:155], v156 offset:2048
	ds_read_b128 v[156:159], v156 offset:3072
	v_lshl_add_u64 v[178:179], s[40:41], 0, v[196:197]
	s_add_i32 m0, s3, 0xc000
	ds_read_b128 v[160:163], v225
	ds_read_b128 v[164:167], v225 offset:1024
	ds_read_b128 v[170:173], v225 offset:2048
	ds_read_b128 v[198:201], v225 offset:3072
	ds_read_b128 v[202:205], v225 offset:4096
	ds_read_b128 v[206:209], v225 offset:5120
	ds_read_b128 v[210:213], v225 offset:6144
	ds_read_b128 v[214:217], v225 offset:7168
	global_load_lds_dwordx4 v[178:179], off
	v_lshl_add_u64 v[178:179], s[40:41], 0, v[194:195]
	s_add_i32 m0, s3, 0xe000
	s_nop 0
	global_load_lds_dwordx4 v[178:179], off
	s_waitcnt vmcnt(8)
	s_waitcnt lgkmcnt(0)
	s_barrier
	s_setprio 1
	s_waitcnt lgkmcnt(0)
	v_mfma_f32_16x16x32_bf16 v[124:127], v[128:131], v[160:163], 0
	v_mfma_f32_16x16x32_bf16 v[120:123], v[136:139], v[160:163], 0
	v_mfma_f32_16x16x32_bf16 v[108:111], v[128:131], v[170:173], 0
	v_mfma_f32_16x16x32_bf16 v[104:107], v[136:139], v[170:173], 0
	v_mfma_f32_16x16x32_bf16 v[92:95], v[128:131], v[202:205], 0
	v_mfma_f32_16x16x32_bf16 v[88:91], v[136:139], v[202:205], 0
	v_mfma_f32_16x16x32_bf16 v[76:79], v[128:131], v[210:213], 0
	v_mfma_f32_16x16x32_bf16 v[72:75], v[136:139], v[210:213], 0
	v_mfma_f32_16x16x32_bf16 v[124:127], v[132:135], v[164:167], v[124:127]
	v_mfma_f32_16x16x32_bf16 v[120:123], v[140:143], v[164:167], v[120:123]
	v_mfma_f32_16x16x32_bf16 v[108:111], v[132:135], v[198:201], v[108:111]
	v_mfma_f32_16x16x32_bf16 v[104:107], v[140:143], v[198:201], v[104:107]
	v_mfma_f32_16x16x32_bf16 v[92:95], v[132:135], v[206:209], v[92:95]
	v_mfma_f32_16x16x32_bf16 v[88:91], v[140:143], v[206:209], v[88:91]
	v_mfma_f32_16x16x32_bf16 v[76:79], v[132:135], v[214:217], v[76:79]
	v_mfma_f32_16x16x32_bf16 v[72:75], v[140:143], v[214:217], v[72:75]
	s_setprio 0
	s_setprio 1
	v_mfma_f32_16x16x32_bf16 v[116:119], v[144:147], v[160:163], 0
	v_mfma_f32_16x16x32_bf16 v[112:115], v[152:155], v[160:163], 0
	v_mfma_f32_16x16x32_bf16 v[100:103], v[144:147], v[170:173], 0
	v_mfma_f32_16x16x32_bf16 v[96:99], v[152:155], v[170:173], 0
	v_mfma_f32_16x16x32_bf16 v[84:87], v[144:147], v[202:205], 0
	v_mfma_f32_16x16x32_bf16 v[80:83], v[152:155], v[202:205], 0
	v_mfma_f32_16x16x32_bf16 v[68:71], v[144:147], v[210:213], 0
	v_mfma_f32_16x16x32_bf16 v[64:67], v[152:155], v[210:213], 0
	v_mfma_f32_16x16x32_bf16 v[116:119], v[148:151], v[164:167], v[116:119]
	v_mfma_f32_16x16x32_bf16 v[112:115], v[156:159], v[164:167], v[112:115]
	v_mfma_f32_16x16x32_bf16 v[100:103], v[148:151], v[198:201], v[100:103]
	v_mfma_f32_16x16x32_bf16 v[96:99], v[156:159], v[198:201], v[96:99]
	v_mfma_f32_16x16x32_bf16 v[84:87], v[148:151], v[206:209], v[84:87]
	v_mfma_f32_16x16x32_bf16 v[80:83], v[156:159], v[206:209], v[80:83]
	v_mfma_f32_16x16x32_bf16 v[68:71], v[148:151], v[214:217], v[68:71]
	v_mfma_f32_16x16x32_bf16 v[64:67], v[156:159], v[214:217], v[64:67]
	s_setprio 0
	s_barrier
	s_add_i32 s64, s64, s2
	v_lshl_add_u64 v[178:179], s[54:55], 0, v[168:169]
	s_mov_b32 m0, s64
	ds_read_b128 v[160:163], v225 offset:16384
	ds_read_b128 v[164:167], v225 offset:17408
	ds_read_b128 v[170:173], v225 offset:18432
	ds_read_b128 v[198:201], v225 offset:19456
	ds_read_b128 v[202:205], v225 offset:20480
	ds_read_b128 v[206:209], v225 offset:21504
	ds_read_b128 v[210:213], v225 offset:22528
	ds_read_b128 v[214:217], v225 offset:23552
	global_load_lds_dwordx4 v[178:179], off
	s_add_i32 m0, s64, 0x2000
	s_add_u32 s64, s54, 0xb0000
	v_lshl_add_u64 v[218:219], s[54:55], 0, v[188:189]
	s_addc_u32 s65, s55, 0
	s_add_i32 s74, s74, s2
	global_load_lds_dwordx4 v[218:219], off
	v_lshl_add_u64 v[220:221], s[64:65], 0, v[168:169]
	s_mov_b32 m0, s74
	s_nop 0
	global_load_lds_dwordx4 v[220:221], off
	v_lshl_add_u64 v[220:221], s[64:65], 0, v[188:189]
	s_add_i32 m0, s74, 0x2000
	s_nop 0
	global_load_lds_dwordx4 v[220:221], off
	v_lshl_add_u64 v[220:221], s[56:57], 0, v[192:193]
	s_mov_b32 m0, s3
	s_nop 0
	global_load_lds_dwordx4 v[220:221], off
	v_lshl_add_u64 v[220:221], s[56:57], 0, v[190:191]
	s_mov_b32 m0, s34
	s_nop 0
	global_load_lds_dwordx4 v[220:221], off
	s_waitcnt vmcnt(8)
	s_waitcnt lgkmcnt(0)
	s_barrier
; #define PG8_STAGE(bufoff, gbase, voff) do { _Pragma("unroll") for (int _i = 0; _i < 2; ++_i) \
;         __builtin_amdgcn_global_load_lds((const unsigned*)((const char*)(gbase) + (voff)[_i]), (PG8_LAS unsigned*)(lds + (bufoff) + ldsw + _i * 8192), 16, 0, 0); } while (0)
; #define PG8_LDA(dst, b, h) do { _Pragma("unroll") for (int m = 0; m < 4; ++m) _Pragma("unroll") for (int k = 0; k < 2; ++k) dst[m][k] = *(const PG8_LAS bf16x8*)(lds + PG8_SA(b, h) + aoff + m * 2048 + k * 1024); } while (0)
; #define PG8_LDB(dst, b, h) do { _Pragma("unroll") for (int n = 0; n < 2; ++n) _Pragma("unroll") for (int k = 0; k < 2; ++k) dst[n][k] = *(const PG8_LAS bf16x8*)(lds + PG8_SB(b, h) + boff + n * 2048 + k * 1024); } while (0)
; #define PG8_MMA(ai, bj, At, Bt) do { __builtin_amdgcn_s_setprio(1); _Pragma("unroll") for (int m = 0; m < 4; ++m) _Pragma("unroll") for (int n = 0; n < 2; ++n) _Pragma("unroll") for (int k = 0; k < 2; ++k) \
;         acc[ai][bj][m][n] = __builtin_amdgcn_mfma_f32_16x16x32_bf16(Bt[n][k], At[m][k], acc[ai][bj][m][n], 0, 0, 0); __builtin_amdgcn_s_setprio(0); } while (0)
; #define PG8_WAIT_V(n) asm volatile("s_waitcnt vmcnt(" #n ")" ::: "memory")
; #define PG8_WAIT_L(n) asm volatile("s_waitcnt lgkmcnt(" #n ")" ::: "memory")
; #define PG8_BAR __builtin_amdgcn_s_barrier()
; #define PG8_SCHED __builtin_amdgcn_sched_barrier(0)
; template <class Epi, class Sched, bool ALIGN_EPI = false, bool SP2 = false>
; __device__ __forceinline__ void gemm_phase(PG8_LAS unsigned char* lds, const Gemm g, const Sched& S, const Epi& E) {
;     ...
;             PG8_WAIT_V(8); PG8_WAIT_L(0); PG8_BAR; PG8_MMA(1, 0, At, B0); PG8_MMA(1, 1, At, B1); PG8_BAR; PG8_SCHED;
;             PG8_LDB(B0, 1, 0); PG8_LDB(B1, 1, 1); PG8_SCHED; PG8_LDA(At, 1, 0); PG8_STAGE(PG8_SA(0, 1), a2 + hstepA, voffA);
;             PG8_WAIT_V(8); PG8_WAIT_L(0); PG8_BAR; PG8_MMA(0, 0, At, B0); PG8_MMA(0, 1, At, B1); PG8_BAR; PG8_SCHED;
	s_setprio 1
	s_waitcnt lgkmcnt(0)
	v_mfma_f32_16x16x32_bf16 v[60:63], v[128:131], v[160:163], 0
	v_mfma_f32_16x16x32_bf16 v[56:59], v[136:139], v[160:163], 0
	v_mfma_f32_16x16x32_bf16 v[44:47], v[128:131], v[170:173], 0
	v_mfma_f32_16x16x32_bf16 v[40:43], v[136:139], v[170:173], 0
	v_mfma_f32_16x16x32_bf16 v[28:31], v[128:131], v[202:205], 0
	v_mfma_f32_16x16x32_bf16 v[24:27], v[136:139], v[202:205], 0
	v_mfma_f32_16x16x32_bf16 v[12:15], v[128:131], v[210:213], 0
	v_mfma_f32_16x16x32_bf16 v[8:11], v[136:139], v[210:213], 0
	v_mfma_f32_16x16x32_bf16 v[60:63], v[132:135], v[164:167], v[60:63]
	v_mfma_f32_16x16x32_bf16 v[56:59], v[140:143], v[164:167], v[56:59]
	v_mfma_f32_16x16x32_bf16 v[44:47], v[132:135], v[198:201], v[44:47]
	v_mfma_f32_16x16x32_bf16 v[40:43], v[140:143], v[198:201], v[40:43]
	v_mfma_f32_16x16x32_bf16 v[28:31], v[132:135], v[206:209], v[28:31]
	v_mfma_f32_16x16x32_bf16 v[24:27], v[140:143], v[206:209], v[24:27]
	v_mfma_f32_16x16x32_bf16 v[12:15], v[132:135], v[214:217], v[12:15]
	v_mfma_f32_16x16x32_bf16 v[8:11], v[140:143], v[214:217], v[8:11]
	s_setprio 0
	s_setprio 1
	v_mfma_f32_16x16x32_bf16 v[52:55], v[144:147], v[160:163], 0
	v_mfma_f32_16x16x32_bf16 v[48:51], v[152:155], v[160:163], 0
	v_mfma_f32_16x16x32_bf16 v[36:39], v[144:147], v[170:173], 0
	v_mfma_f32_16x16x32_bf16 v[32:35], v[152:155], v[170:173], 0
	v_mfma_f32_16x16x32_bf16 v[20:23], v[144:147], v[202:205], 0
	v_mfma_f32_16x16x32_bf16 v[16:19], v[152:155], v[202:205], 0
	v_mfma_f32_16x16x32_bf16 v[4:7], v[144:147], v[210:213], 0
	v_mfma_f32_16x16x32_bf16 v[0:3], v[152:155], v[210:213], 0
	v_mfma_f32_16x16x32_bf16 v[52:55], v[148:151], v[164:167], v[52:55]
	v_mfma_f32_16x16x32_bf16 v[48:51], v[156:159], v[164:167], v[48:51]
	v_mfma_f32_16x16x32_bf16 v[36:39], v[148:151], v[198:201], v[36:39]
	v_mfma_f32_16x16x32_bf16 v[32:35], v[156:159], v[198:201], v[32:35]
	v_mfma_f32_16x16x32_bf16 v[20:23], v[148:151], v[206:209], v[20:23]
	v_mfma_f32_16x16x32_bf16 v[16:19], v[156:159], v[206:209], v[16:19]
	v_mfma_f32_16x16x32_bf16 v[4:7], v[148:151], v[214:217], v[4:7]
	v_mfma_f32_16x16x32_bf16 v[0:3], v[156:159], v[214:217], v[0:3]
	s_setprio 0
	s_barrier
	s_add_i32 s64, 0, 0x18000
	s_add_i32 s65, 0, 0x1c000
	v_add_u32_e32 v140, s64, v224
	v_add_u32_e32 v156, s65, v224
	ds_read_b128 v[128:131], v140
	ds_read_b128 v[132:135], v140 offset:1024
	ds_read_b128 v[136:139], v140 offset:2048
	ds_read_b128 v[140:143], v140 offset:3072
	ds_read_b128 v[144:147], v156
	ds_read_b128 v[148:151], v156 offset:1024
	ds_read_b128 v[152:155], v156 offset:2048
	ds_read_b128 v[156:159], v156 offset:3072
	s_add_u32 s56, s56, 0xb0000
	s_addc_u32 s57, s57, 0
	s_mov_b32 m0, s35
	v_lshl_add_u64 v[220:221], s[56:57], 0, v[192:193]
	ds_read_b128 v[160:163], v225 offset:32768
	ds_read_b128 v[164:167], v225 offset:33792
	ds_read_b128 v[170:173], v225 offset:34816
	ds_read_b128 v[198:201], v225 offset:35840
	ds_read_b128 v[202:205], v225 offset:36864
	ds_read_b128 v[206:209], v225 offset:37888
	ds_read_b128 v[210:213], v225 offset:38912
	ds_read_b128 v[214:217], v225 offset:39936
	global_load_lds_dwordx4 v[220:221], off
	v_lshl_add_u64 v[220:221], s[56:57], 0, v[190:191]
	s_mov_b32 m0, s60
	s_nop 0
	global_load_lds_dwordx4 v[220:221], off
	s_waitcnt vmcnt(8)
	s_waitcnt lgkmcnt(0)
	s_barrier
	s_setprio 1
	s_waitcnt lgkmcnt(0)
	v_mfma_f32_16x16x32_bf16 v[124:127], v[128:131], v[160:163], v[124:127]
	v_mfma_f32_16x16x32_bf16 v[120:123], v[136:139], v[160:163], v[120:123]
	v_mfma_f32_16x16x32_bf16 v[108:111], v[128:131], v[170:173], v[108:111]
	v_mfma_f32_16x16x32_bf16 v[104:107], v[136:139], v[170:173], v[104:107]
	v_mfma_f32_16x16x32_bf16 v[92:95], v[128:131], v[202:205], v[92:95]
	v_mfma_f32_16x16x32_bf16 v[88:91], v[136:139], v[202:205], v[88:91]
	v_mfma_f32_16x16x32_bf16 v[76:79], v[128:131], v[210:213], v[76:79]
	v_mfma_f32_16x16x32_bf16 v[72:75], v[136:139], v[210:213], v[72:75]
	v_mfma_f32_16x16x32_bf16 v[124:127], v[132:135], v[164:167], v[124:127]
	v_mfma_f32_16x16x32_bf16 v[120:123], v[140:143], v[164:167], v[120:123]
	v_mfma_f32_16x16x32_bf16 v[108:111], v[132:135], v[198:201], v[108:111]
	v_mfma_f32_16x16x32_bf16 v[104:107], v[140:143], v[198:201], v[104:107]
	v_mfma_f32_16x16x32_bf16 v[92:95], v[132:135], v[206:209], v[92:95]
	v_mfma_f32_16x16x32_bf16 v[88:91], v[140:143], v[206:209], v[88:91]
	v_mfma_f32_16x16x32_bf16 v[76:79], v[132:135], v[214:217], v[76:79]
	v_mfma_f32_16x16x32_bf16 v[72:75], v[140:143], v[214:217], v[72:75]
	s_setprio 0
	s_setprio 1
	v_mfma_f32_16x16x32_bf16 v[116:119], v[144:147], v[160:163], v[116:119]
	v_mfma_f32_16x16x32_bf16 v[112:115], v[152:155], v[160:163], v[112:115]
	v_mfma_f32_16x16x32_bf16 v[100:103], v[144:147], v[170:173], v[100:103]
	v_mfma_f32_16x16x32_bf16 v[96:99], v[152:155], v[170:173], v[96:99]
	v_mfma_f32_16x16x32_bf16 v[84:87], v[144:147], v[202:205], v[84:87]
	v_mfma_f32_16x16x32_bf16 v[80:83], v[152:155], v[202:205], v[80:83]
	v_mfma_f32_16x16x32_bf16 v[68:71], v[144:147], v[210:213], v[68:71]
	v_mfma_f32_16x16x32_bf16 v[64:67], v[152:155], v[210:213], v[64:67]
	v_mfma_f32_16x16x32_bf16 v[116:119], v[148:151], v[164:167], v[116:119]
	v_mfma_f32_16x16x32_bf16 v[112:115], v[156:159], v[164:167], v[112:115]
	v_mfma_f32_16x16x32_bf16 v[100:103], v[148:151], v[198:201], v[100:103]
	v_mfma_f32_16x16x32_bf16 v[96:99], v[156:159], v[198:201], v[96:99]
	v_mfma_f32_16x16x32_bf16 v[84:87], v[148:151], v[206:209], v[84:87]
	v_mfma_f32_16x16x32_bf16 v[80:83], v[156:159], v[206:209], v[80:83]
	v_mfma_f32_16x16x32_bf16 v[68:71], v[148:151], v[214:217], v[68:71]
	v_mfma_f32_16x16x32_bf16 v[64:67], v[156:159], v[214:217], v[64:67]
	s_setprio 0
	s_barrier
; #define PG8_STAGE(bufoff, gbase, voff) do { _Pragma("unroll") for (int _i = 0; _i < 2; ++_i) \
;         __builtin_amdgcn_global_load_lds((const unsigned*)((const char*)(gbase) + (voff)[_i]), (PG8_LAS unsigned*)(lds + (bufoff) + ldsw + _i * 8192), 16, 0, 0); } while (0)
; #define PG8_LDA(dst, b, h) do { _Pragma("unroll") for (int m = 0; m < 4; ++m) _Pragma("unroll") for (int k = 0; k < 2; ++k) dst[m][k] = *(const PG8_LAS bf16x8*)(lds + PG8_SA(b, h) + aoff + m * 2048 + k * 1024); } while (0)
; #define PG8_MMA(ai, bj, At, Bt) do { __builtin_amdgcn_s_setprio(1); _Pragma("unroll") for (int m = 0; m < 4; ++m) _Pragma("unroll") for (int n = 0; n < 2; ++n) _Pragma("unroll") for (int k = 0; k < 2; ++k) \
;         acc[ai][bj][m][n] = __builtin_amdgcn_mfma_f32_16x16x32_bf16(Bt[n][k], At[m][k], acc[ai][bj][m][n], 0, 0, 0); __builtin_amdgcn_s_setprio(0); } while (0)
; #define PG8_WAIT_V(n) asm volatile("s_waitcnt vmcnt(" #n ")" ::: "memory")
; #define PG8_WAIT_L(n) asm volatile("s_waitcnt lgkmcnt(" #n ")" ::: "memory")
; #define PG8_BAR __builtin_amdgcn_s_barrier()
; #define PG8_SCHED __builtin_amdgcn_sched_barrier(0)
; template <class Epi, class Sched, bool ALIGN_EPI = false, bool SP2 = false>
; __device__ __forceinline__ void gemm_phase(PG8_LAS unsigned char* lds, const Gemm g, const Sched& S, const Epi& E) {
;     ...
;         for (int t = 0; t < nt; t += 2) {
;             const bool last = (t == nt - 2);
;             const char* a1 = cA + (size_t)(t + 1) * kstepA;
;             const char* a2 = last ? nA : cA + (size_t)(t + 2) * kstepA; const char* b2 = last ? nB : cB + (size_t)(t + 2) * kstep;
;             const char* a3 = a2 + kstepA; const char* b3 = b2 + kstep;
;     ...
;             PG8_LDA(At, 1, 1); PG8_STAGE(PG8_SB(1, 0), b3, voffB); PG8_STAGE(PG8_SB(1, 1), b3 + hstep, voffB); PG8_STAGE(PG8_SA(1, 0), a3, voffA);
;             PG8_WAIT_V(8); PG8_WAIT_L(0); PG8_BAR; PG8_MMA(1, 0, At, B0); PG8_MMA(1, 1, At, B1); PG8_BAR; PG8_SCHED;
	s_add_i32 s56, s64, s2
	v_lshl_add_u64 v[178:179], v[178:179], 0, s[30:31]
	s_mov_b32 m0, s56
	ds_read_b128 v[160:163], v225 offset:49152
	ds_read_b128 v[164:167], v225 offset:50176
	ds_read_b128 v[170:173], v225 offset:51200
	ds_read_b128 v[198:201], v225 offset:52224
	ds_read_b128 v[202:205], v225 offset:53248
	ds_read_b128 v[206:209], v225 offset:54272
	ds_read_b128 v[210:213], v225 offset:55296
	ds_read_b128 v[214:217], v225 offset:56320
	global_load_lds_dwordx4 v[178:179], off
	s_add_i32 m0, s56, 0x2000
	s_add_u32 s54, s54, 0xb0080
	v_lshl_add_u64 v[178:179], v[218:219], 0, s[30:31]
	s_addc_u32 s55, s55, 0
	s_add_i32 s56, s65, s2
	global_load_lds_dwordx4 v[178:179], off
	v_lshl_add_u64 v[178:179], s[54:55], 0, v[168:169]
	s_mov_b32 m0, s56
	s_nop 0
	global_load_lds_dwordx4 v[178:179], off
	v_lshl_add_u64 v[178:179], s[54:55], 0, v[188:189]
	s_add_i32 m0, s56, 0x2000
	s_nop 0
	global_load_lds_dwordx4 v[178:179], off
	v_lshl_add_u64 v[178:179], s[52:53], 0, v[192:193]
	s_mov_b32 m0, s69
	s_nop 0
	global_load_lds_dwordx4 v[178:179], off
	v_lshl_add_u64 v[178:179], s[52:53], 0, v[190:191]
	s_mov_b32 m0, s73
	s_nop 0
	global_load_lds_dwordx4 v[178:179], off
	s_waitcnt vmcnt(8)
	s_waitcnt lgkmcnt(0)
	s_barrier
	s_setprio 1
	s_waitcnt lgkmcnt(0)
	v_mfma_f32_16x16x32_bf16 v[60:63], v[128:131], v[160:163], v[60:63]
	v_mfma_f32_16x16x32_bf16 v[56:59], v[136:139], v[160:163], v[56:59]
	v_mfma_f32_16x16x32_bf16 v[44:47], v[128:131], v[170:173], v[44:47]
	v_mfma_f32_16x16x32_bf16 v[40:43], v[136:139], v[170:173], v[40:43]
	v_mfma_f32_16x16x32_bf16 v[28:31], v[128:131], v[202:205], v[28:31]
	v_mfma_f32_16x16x32_bf16 v[24:27], v[136:139], v[202:205], v[24:27]
	v_mfma_f32_16x16x32_bf16 v[12:15], v[128:131], v[210:213], v[12:15]
	v_mfma_f32_16x16x32_bf16 v[8:11], v[136:139], v[210:213], v[8:11]
	v_mfma_f32_16x16x32_bf16 v[60:63], v[132:135], v[164:167], v[60:63]
	v_mfma_f32_16x16x32_bf16 v[56:59], v[140:143], v[164:167], v[56:59]
	v_mfma_f32_16x16x32_bf16 v[44:47], v[132:135], v[198:201], v[44:47]
	v_mfma_f32_16x16x32_bf16 v[40:43], v[140:143], v[198:201], v[40:43]
	v_mfma_f32_16x16x32_bf16 v[28:31], v[132:135], v[206:209], v[28:31]
	v_mfma_f32_16x16x32_bf16 v[24:27], v[140:143], v[206:209], v[24:27]
	v_mfma_f32_16x16x32_bf16 v[12:15], v[132:135], v[214:217], v[12:15]
	v_mfma_f32_16x16x32_bf16 v[8:11], v[140:143], v[214:217], v[8:11]
	s_setprio 0
	s_setprio 1
	v_mfma_f32_16x16x32_bf16 v[52:55], v[144:147], v[160:163], v[52:55]
	v_mfma_f32_16x16x32_bf16 v[48:51], v[152:155], v[160:163], v[48:51]
	v_mfma_f32_16x16x32_bf16 v[36:39], v[144:147], v[170:173], v[36:39]
	v_mfma_f32_16x16x32_bf16 v[32:35], v[152:155], v[170:173], v[32:35]
	v_mfma_f32_16x16x32_bf16 v[20:23], v[144:147], v[202:205], v[20:23]
	v_mfma_f32_16x16x32_bf16 v[16:19], v[152:155], v[202:205], v[16:19]
	v_mfma_f32_16x16x32_bf16 v[4:7], v[144:147], v[210:213], v[4:7]
	v_mfma_f32_16x16x32_bf16 v[0:3], v[152:155], v[210:213], v[0:3]
	v_mfma_f32_16x16x32_bf16 v[52:55], v[148:151], v[164:167], v[52:55]
	v_mfma_f32_16x16x32_bf16 v[48:51], v[156:159], v[164:167], v[48:51]
	v_mfma_f32_16x16x32_bf16 v[36:39], v[148:151], v[198:201], v[36:39]
	v_mfma_f32_16x16x32_bf16 v[32:35], v[156:159], v[198:201], v[32:35]
	v_mfma_f32_16x16x32_bf16 v[20:23], v[148:151], v[206:209], v[20:23]
	v_mfma_f32_16x16x32_bf16 v[16:19], v[156:159], v[206:209], v[16:19]
	v_mfma_f32_16x16x32_bf16 v[4:7], v[148:151], v[214:217], v[4:7]
	v_mfma_f32_16x16x32_bf16 v[0:3], v[156:159], v[214:217], v[0:3]
	s_setprio 0
	s_barrier
	s_add_i32 s7, s7, 2
	s_add_u32 s5, s5, 0x100
	s_addc_u32 s6, s6, 0
	s_add_u32 s40, s40, 0x8000
	s_addc_u32 s41, s41, 0

; #define PG8_STAGE(bufoff, gbase, voff) do { _Pragma("unroll") for (int _i = 0; _i < 2; ++_i) \
;         __builtin_amdgcn_global_load_lds((const unsigned*)((const char*)(gbase) + (voff)[_i]), (PG8_LAS unsigned*)(lds + (bufoff) + ldsw + _i * 8192), 16, 0, 0); } while (0)
; #define PG8_LDA(dst, b, h) do { _Pragma("unroll") for (int m = 0; m < 4; ++m) _Pragma("unroll") for (int k = 0; k < 2; ++k) dst[m][k] = *(const PG8_LAS bf16x8*)(lds + PG8_SA(b, h) + aoff + m * 2048 + k * 1024); } while (0)
; #define PG8_LDB(dst, b, h) do { _Pragma("unroll") for (int n = 0; n < 2; ++n) _Pragma("unroll") for (int k = 0; k < 2; ++k) dst[n][k] = *(const PG8_LAS bf16x8*)(lds + PG8_SB(b, h) + boff + n * 2048 + k * 1024); } while (0)
; #define PG8_WAIT_V(n) asm volatile("s_waitcnt vmcnt(" #n ")" ::: "memory")
; #define PG8_WAIT_L(n) asm volatile("s_waitcnt lgkmcnt(" #n ")" ::: "memory")
; #define PG8_BAR __builtin_amdgcn_s_barrier()
; #define PG8_SCHED __builtin_amdgcn_sched_barrier(0)
; template <class Epi, class Sched, bool ALIGN_EPI = false, bool SP2 = false>
; __device__ __forceinline__ void gemm_phase(PG8_LAS unsigned char* lds, const Gemm g, const Sched& S, const Epi& E) {
;     ...
;         const bool has_next = S.next(ui + 1, nxt);
;         const char* nA = has_next ? (const char*)g.A + (size_t)nxt.pm * tstepA : cA; const char* nB = has_next ? (const char*)g.Bt + (size_t)nxt.pn * tstep : cB;
;         for (int t = 0; t < nt; t += 2) {
;             const bool last = (t == nt - 2);
;             const char* a1 = cA + (size_t)(t + 1) * kstepA;
;             const char* a2 = last ? nA : cA + (size_t)(t + 2) * kstepA; const char* b2 = last ? nB : cB + (size_t)(t + 2) * kstep;
;             const char* a3 = a2 + kstepA; const char* b3 = b2 + kstep;
;             if (last && has_next) S.a_ready(nxt);
;             if constexpr (SP2) {
;             PG8_LDB(B0, 0, 0); PG8_LDB(B1, 0, 1); PG8_SCHED; PG8_LDA(At, 0, 0); PG8_STAGE(PG8_SA(1, 1), a1 + hstepA, voffA);
;             PG8_WAIT_V(8); PG8_WAIT_L(0); PG8_BAR; PG8_MMA(0, 0, At, B0); PG8_MMA(0, 1, At, B1); PG8_BAR; PG8_SCHED;
;             PG8_LDA(At, 0, 1); PG8_STAGE(PG8_SB(0, 0), b2, voffB); PG8_STAGE(PG8_SB(0, 1), b2 + hstep, voffB); PG8_STAGE(PG8_SA(0, 0), a2, voffA);
;             PG8_WAIT_V(8); PG8_WAIT_L(0); PG8_BAR; PG8_MMA(1, 0, At, B0); PG8_MMA(1, 1, At, B1); PG8_BAR; PG8_SCHED;
.LBB0_973:
	s_add_u32 s5, s48, 0x100
	s_addc_u32 s6, s49, 0
	s_add_u32 s38, s50, 0xb4000
	s_addc_u32 s39, s51, 0
	s_mov_b32 s7, -2
	s_add_u32 s48, s38, 0xfff54000
	s_addc_u32 s49, s39, -1
	s_cmp_eq_u32 s7, 40
	s_cselect_b32 s52, s44, s48
	s_cselect_b32 s53, s45, s49
	s_cselect_b32 s50, s46, s5
	s_cselect_b32 s51, s47, s6
	s_add_u32 s48, s52, 0x4000
	s_addc_u32 s49, s53, 0
	s_add_i32 s64, 0, 0x10000
	s_add_i32 s74, 0, 0x14000
	v_add_u32_e32 v140, s64, v236
	v_add_u32_e32 v156, s74, v236
	ds_read_b128 v[128:131], v140
	ds_read_b128 v[132:135], v140 offset:1024
	ds_read_b128 v[136:139], v140 offset:2048
	ds_read_b128 v[140:143], v140 offset:3072
	ds_read_b128 v[144:147], v156
	ds_read_b128 v[148:151], v156 offset:1024
	ds_read_b128 v[152:155], v156 offset:2048
	ds_read_b128 v[156:159], v156 offset:3072
	v_lshl_add_u64 v[178:179], s[38:39], 0, v[196:197]
	s_add_i32 m0, s3, 0xc000
	ds_read_b128 v[160:163], v237
	ds_read_b128 v[164:167], v237 offset:1024
	ds_read_b128 v[170:173], v237 offset:2048
	ds_read_b128 v[198:201], v237 offset:3072
	ds_read_b128 v[202:205], v237 offset:4096
	ds_read_b128 v[206:209], v237 offset:5120
	ds_read_b128 v[210:213], v237 offset:6144
	ds_read_b128 v[214:217], v237 offset:7168
	global_load_lds_dwordx4 v[178:179], off
	v_lshl_add_u64 v[178:179], s[38:39], 0, v[194:195]
	s_add_i32 m0, s3, 0xe000
	s_nop 0
	global_load_lds_dwordx4 v[178:179], off
	s_waitcnt vmcnt(8)
	s_waitcnt lgkmcnt(0)
	s_barrier
	s_setprio 1
	s_waitcnt lgkmcnt(0)
	v_mfma_f32_16x16x32_bf16 v[124:127], v[128:131], v[160:163], 0
	v_mfma_f32_16x16x32_bf16 v[120:123], v[136:139], v[160:163], 0
	v_mfma_f32_16x16x32_bf16 v[108:111], v[128:131], v[170:173], 0
	v_mfma_f32_16x16x32_bf16 v[104:107], v[136:139], v[170:173], 0
	v_mfma_f32_16x16x32_bf16 v[92:95], v[128:131], v[202:205], 0
	v_mfma_f32_16x16x32_bf16 v[88:91], v[136:139], v[202:205], 0
	v_mfma_f32_16x16x32_bf16 v[76:79], v[128:131], v[210:213], 0
	v_mfma_f32_16x16x32_bf16 v[72:75], v[136:139], v[210:213], 0
	v_mfma_f32_16x16x32_bf16 v[124:127], v[132:135], v[164:167], v[124:127]
	v_mfma_f32_16x16x32_bf16 v[120:123], v[140:143], v[164:167], v[120:123]
	v_mfma_f32_16x16x32_bf16 v[108:111], v[132:135], v[198:201], v[108:111]
	v_mfma_f32_16x16x32_bf16 v[104:107], v[140:143], v[198:201], v[104:107]
	v_mfma_f32_16x16x32_bf16 v[92:95], v[132:135], v[206:209], v[92:95]
	v_mfma_f32_16x16x32_bf16 v[88:91], v[140:143], v[206:209], v[88:91]
	v_mfma_f32_16x16x32_bf16 v[76:79], v[132:135], v[214:217], v[76:79]
	v_mfma_f32_16x16x32_bf16 v[72:75], v[140:143], v[214:217], v[72:75]
	s_setprio 0
	s_setprio 1
	v_mfma_f32_16x16x32_bf16 v[116:119], v[144:147], v[160:163], 0
	v_mfma_f32_16x16x32_bf16 v[112:115], v[152:155], v[160:163], 0
	v_mfma_f32_16x16x32_bf16 v[100:103], v[144:147], v[170:173], 0
	v_mfma_f32_16x16x32_bf16 v[96:99], v[152:155], v[170:173], 0
	v_mfma_f32_16x16x32_bf16 v[84:87], v[144:147], v[202:205], 0
	v_mfma_f32_16x16x32_bf16 v[80:83], v[152:155], v[202:205], 0
	v_mfma_f32_16x16x32_bf16 v[68:71], v[144:147], v[210:213], 0
	v_mfma_f32_16x16x32_bf16 v[64:67], v[152:155], v[210:213], 0
	v_mfma_f32_16x16x32_bf16 v[116:119], v[148:151], v[164:167], v[116:119]
	v_mfma_f32_16x16x32_bf16 v[112:115], v[156:159], v[164:167], v[112:115]
	v_mfma_f32_16x16x32_bf16 v[100:103], v[148:151], v[198:201], v[100:103]
	v_mfma_f32_16x16x32_bf16 v[96:99], v[156:159], v[198:201], v[96:99]
	v_mfma_f32_16x16x32_bf16 v[84:87], v[148:151], v[206:209], v[84:87]
	v_mfma_f32_16x16x32_bf16 v[80:83], v[156:159], v[206:209], v[80:83]
	v_mfma_f32_16x16x32_bf16 v[68:71], v[148:151], v[214:217], v[68:71]
	v_mfma_f32_16x16x32_bf16 v[64:67], v[156:159], v[214:217], v[64:67]
	s_setprio 0
	s_barrier
	s_add_i32 s64, s64, s2
	v_lshl_add_u64 v[178:179], s[50:51], 0, v[168:169]
	s_mov_b32 m0, s64
	ds_read_b128 v[160:163], v237 offset:16384
	ds_read_b128 v[164:167], v237 offset:17408
	ds_read_b128 v[170:173], v237 offset:18432
	ds_read_b128 v[198:201], v237 offset:19456
	ds_read_b128 v[202:205], v237 offset:20480
	ds_read_b128 v[206:209], v237 offset:21504
	ds_read_b128 v[210:213], v237 offset:22528
	ds_read_b128 v[214:217], v237 offset:23552
	global_load_lds_dwordx4 v[178:179], off
	s_add_i32 m0, s64, 0x2000
	s_add_u32 s64, s50, 0xb0000
	v_lshl_add_u64 v[218:219], s[50:51], 0, v[188:189]
	s_addc_u32 s65, s51, 0
	s_add_i32 s74, s74, s2
	global_load_lds_dwordx4 v[218:219], off
	v_lshl_add_u64 v[220:221], s[64:65], 0, v[168:169]
	s_mov_b32 m0, s74
	s_nop 0
	global_load_lds_dwordx4 v[220:221], off
	v_lshl_add_u64 v[220:221], s[64:65], 0, v[188:189]
	s_add_i32 m0, s74, 0x2000
	s_nop 0
	global_load_lds_dwordx4 v[220:221], off
	v_lshl_add_u64 v[220:221], s[52:53], 0, v[192:193]
	s_mov_b32 m0, s3
	s_nop 0
	global_load_lds_dwordx4 v[220:221], off
	v_lshl_add_u64 v[220:221], s[52:53], 0, v[190:191]
	s_mov_b32 m0, s34
	s_nop 0
	global_load_lds_dwordx4 v[220:221], off
	s_waitcnt vmcnt(8)
	s_waitcnt lgkmcnt(0)
	s_barrier
; #define PG8_STAGE(bufoff, gbase, voff) do { _Pragma("unroll") for (int _i = 0; _i < 2; ++_i) \
;         __builtin_amdgcn_global_load_lds((const unsigned*)((const char*)(gbase) + (voff)[_i]), (PG8_LAS unsigned*)(lds + (bufoff) + ldsw + _i * 8192), 16, 0, 0); } while (0)
; #define PG8_LDA(dst, b, h) do { _Pragma("unroll") for (int m = 0; m < 4; ++m) _Pragma("unroll") for (int k = 0; k < 2; ++k) dst[m][k] = *(const PG8_LAS bf16x8*)(lds + PG8_SA(b, h) + aoff + m * 2048 + k * 1024); } while (0)
; #define PG8_LDB(dst, b, h) do { _Pragma("unroll") for (int n = 0; n < 2; ++n) _Pragma("unroll") for (int k = 0; k < 2; ++k) dst[n][k] = *(const PG8_LAS bf16x8*)(lds + PG8_SB(b, h) + boff + n * 2048 + k * 1024); } while (0)
; #define PG8_MMA(ai, bj, At, Bt) do { __builtin_amdgcn_s_setprio(1); _Pragma("unroll") for (int m = 0; m < 4; ++m) _Pragma("unroll") for (int n = 0; n < 2; ++n) _Pragma("unroll") for (int k = 0; k < 2; ++k) \
;         acc[ai][bj][m][n] = __builtin_amdgcn_mfma_f32_16x16x32_bf16(Bt[n][k], At[m][k], acc[ai][bj][m][n], 0, 0, 0); __builtin_amdgcn_s_setprio(0); } while (0)
; #define PG8_WAIT_V(n) asm volatile("s_waitcnt vmcnt(" #n ")" ::: "memory")
; #define PG8_WAIT_L(n) asm volatile("s_waitcnt lgkmcnt(" #n ")" ::: "memory")
; #define PG8_BAR __builtin_amdgcn_s_barrier()
; #define PG8_SCHED __builtin_amdgcn_sched_barrier(0)
; template <class Epi, class Sched, bool ALIGN_EPI = false, bool SP2 = false>
; __device__ __forceinline__ void gemm_phase(PG8_LAS unsigned char* lds, const Gemm g, const Sched& S, const Epi& E) {
;     ...
;             PG8_WAIT_V(8); PG8_WAIT_L(0); PG8_BAR; PG8_MMA(1, 0, At, B0); PG8_MMA(1, 1, At, B1); PG8_BAR; PG8_SCHED;
;             PG8_LDB(B0, 1, 0); PG8_LDB(B1, 1, 1); PG8_SCHED; PG8_LDA(At, 1, 0); PG8_STAGE(PG8_SA(0, 1), a2 + hstepA, voffA);
;             PG8_WAIT_V(8); PG8_WAIT_L(0); PG8_BAR; PG8_MMA(0, 0, At, B0); PG8_MMA(0, 1, At, B1); PG8_BAR; PG8_SCHED;
	s_setprio 1
	s_waitcnt lgkmcnt(0)
	v_mfma_f32_16x16x32_bf16 v[60:63], v[128:131], v[160:163], 0
	v_mfma_f32_16x16x32_bf16 v[56:59], v[136:139], v[160:163], 0
	v_mfma_f32_16x16x32_bf16 v[44:47], v[128:131], v[170:173], 0
	v_mfma_f32_16x16x32_bf16 v[40:43], v[136:139], v[170:173], 0
	v_mfma_f32_16x16x32_bf16 v[28:31], v[128:131], v[202:205], 0
	v_mfma_f32_16x16x32_bf16 v[24:27], v[136:139], v[202:205], 0
	v_mfma_f32_16x16x32_bf16 v[12:15], v[128:131], v[210:213], 0
	v_mfma_f32_16x16x32_bf16 v[8:11], v[136:139], v[210:213], 0
	v_mfma_f32_16x16x32_bf16 v[60:63], v[132:135], v[164:167], v[60:63]
	v_mfma_f32_16x16x32_bf16 v[56:59], v[140:143], v[164:167], v[56:59]
	v_mfma_f32_16x16x32_bf16 v[44:47], v[132:135], v[198:201], v[44:47]
	v_mfma_f32_16x16x32_bf16 v[40:43], v[140:143], v[198:201], v[40:43]
	v_mfma_f32_16x16x32_bf16 v[28:31], v[132:135], v[206:209], v[28:31]
	v_mfma_f32_16x16x32_bf16 v[24:27], v[140:143], v[206:209], v[24:27]
	v_mfma_f32_16x16x32_bf16 v[12:15], v[132:135], v[214:217], v[12:15]
	v_mfma_f32_16x16x32_bf16 v[8:11], v[140:143], v[214:217], v[8:11]
	s_setprio 0
	s_setprio 1
	v_mfma_f32_16x16x32_bf16 v[52:55], v[144:147], v[160:163], 0
	v_mfma_f32_16x16x32_bf16 v[48:51], v[152:155], v[160:163], 0
	v_mfma_f32_16x16x32_bf16 v[36:39], v[144:147], v[170:173], 0
	v_mfma_f32_16x16x32_bf16 v[32:35], v[152:155], v[170:173], 0
	v_mfma_f32_16x16x32_bf16 v[20:23], v[144:147], v[202:205], 0
	v_mfma_f32_16x16x32_bf16 v[16:19], v[152:155], v[202:205], 0
	v_mfma_f32_16x16x32_bf16 v[4:7], v[144:147], v[210:213], 0
	v_mfma_f32_16x16x32_bf16 v[0:3], v[152:155], v[210:213], 0
	v_mfma_f32_16x16x32_bf16 v[52:55], v[148:151], v[164:167], v[52:55]
	v_mfma_f32_16x16x32_bf16 v[48:51], v[156:159], v[164:167], v[48:51]
	v_mfma_f32_16x16x32_bf16 v[36:39], v[148:151], v[198:201], v[36:39]
	v_mfma_f32_16x16x32_bf16 v[32:35], v[156:159], v[198:201], v[32:35]
	v_mfma_f32_16x16x32_bf16 v[20:23], v[148:151], v[206:209], v[20:23]
	v_mfma_f32_16x16x32_bf16 v[16:19], v[156:159], v[206:209], v[16:19]
	v_mfma_f32_16x16x32_bf16 v[4:7], v[148:151], v[214:217], v[4:7]
	v_mfma_f32_16x16x32_bf16 v[0:3], v[156:159], v[214:217], v[0:3]
	s_setprio 0
	s_barrier
	s_add_i32 s64, 0, 0x18000
	s_add_i32 s65, 0, 0x1c000
	v_add_u32_e32 v140, s64, v236
	v_add_u32_e32 v156, s65, v236
	ds_read_b128 v[128:131], v140
	ds_read_b128 v[132:135], v140 offset:1024
	ds_read_b128 v[136:139], v140 offset:2048
	ds_read_b128 v[140:143], v140 offset:3072
	ds_read_b128 v[144:147], v156
	ds_read_b128 v[148:151], v156 offset:1024
	ds_read_b128 v[152:155], v156 offset:2048
	ds_read_b128 v[156:159], v156 offset:3072
	s_add_u32 s52, s52, 0xb0000
	s_addc_u32 s53, s53, 0
	s_mov_b32 m0, s35
	v_lshl_add_u64 v[220:221], s[52:53], 0, v[192:193]
	ds_read_b128 v[160:163], v237 offset:32768
	ds_read_b128 v[164:167], v237 offset:33792
	ds_read_b128 v[170:173], v237 offset:34816
	ds_read_b128 v[198:201], v237 offset:35840
	ds_read_b128 v[202:205], v237 offset:36864
	ds_read_b128 v[206:209], v237 offset:37888
	ds_read_b128 v[210:213], v237 offset:38912
	ds_read_b128 v[214:217], v237 offset:39936
	global_load_lds_dwordx4 v[220:221], off
	v_lshl_add_u64 v[220:221], s[52:53], 0, v[190:191]
	s_mov_b32 m0, s54
	s_nop 0
	global_load_lds_dwordx4 v[220:221], off
	s_waitcnt vmcnt(8)
	s_waitcnt lgkmcnt(0)
	s_barrier
	s_setprio 1
	s_waitcnt lgkmcnt(0)
	v_mfma_f32_16x16x32_bf16 v[124:127], v[128:131], v[160:163], v[124:127]
	v_mfma_f32_16x16x32_bf16 v[120:123], v[136:139], v[160:163], v[120:123]
	v_mfma_f32_16x16x32_bf16 v[108:111], v[128:131], v[170:173], v[108:111]
	v_mfma_f32_16x16x32_bf16 v[104:107], v[136:139], v[170:173], v[104:107]
	v_mfma_f32_16x16x32_bf16 v[92:95], v[128:131], v[202:205], v[92:95]
	v_mfma_f32_16x16x32_bf16 v[88:91], v[136:139], v[202:205], v[88:91]
	v_mfma_f32_16x16x32_bf16 v[76:79], v[128:131], v[210:213], v[76:79]
	v_mfma_f32_16x16x32_bf16 v[72:75], v[136:139], v[210:213], v[72:75]
	v_mfma_f32_16x16x32_bf16 v[124:127], v[132:135], v[164:167], v[124:127]
	v_mfma_f32_16x16x32_bf16 v[120:123], v[140:143], v[164:167], v[120:123]
	v_mfma_f32_16x16x32_bf16 v[108:111], v[132:135], v[198:201], v[108:111]
	v_mfma_f32_16x16x32_bf16 v[104:107], v[140:143], v[198:201], v[104:107]
	v_mfma_f32_16x16x32_bf16 v[92:95], v[132:135], v[206:209], v[92:95]
	v_mfma_f32_16x16x32_bf16 v[88:91], v[140:143], v[206:209], v[88:91]
	v_mfma_f32_16x16x32_bf16 v[76:79], v[132:135], v[214:217], v[76:79]
	v_mfma_f32_16x16x32_bf16 v[72:75], v[140:143], v[214:217], v[72:75]
	s_setprio 0
	s_setprio 1
	v_mfma_f32_16x16x32_bf16 v[116:119], v[144:147], v[160:163], v[116:119]
	v_mfma_f32_16x16x32_bf16 v[112:115], v[152:155], v[160:163], v[112:115]
	v_mfma_f32_16x16x32_bf16 v[100:103], v[144:147], v[170:173], v[100:103]
	v_mfma_f32_16x16x32_bf16 v[96:99], v[152:155], v[170:173], v[96:99]
	v_mfma_f32_16x16x32_bf16 v[84:87], v[144:147], v[202:205], v[84:87]
	v_mfma_f32_16x16x32_bf16 v[80:83], v[152:155], v[202:205], v[80:83]
	v_mfma_f32_16x16x32_bf16 v[68:71], v[144:147], v[210:213], v[68:71]
	v_mfma_f32_16x16x32_bf16 v[64:67], v[152:155], v[210:213], v[64:67]
	v_mfma_f32_16x16x32_bf16 v[116:119], v[148:151], v[164:167], v[116:119]
	v_mfma_f32_16x16x32_bf16 v[112:115], v[156:159], v[164:167], v[112:115]
	v_mfma_f32_16x16x32_bf16 v[100:103], v[148:151], v[198:201], v[100:103]
	v_mfma_f32_16x16x32_bf16 v[96:99], v[156:159], v[198:201], v[96:99]
	v_mfma_f32_16x16x32_bf16 v[84:87], v[148:151], v[206:209], v[84:87]
	v_mfma_f32_16x16x32_bf16 v[80:83], v[156:159], v[206:209], v[80:83]
	v_mfma_f32_16x16x32_bf16 v[68:71], v[148:151], v[214:217], v[68:71]
	v_mfma_f32_16x16x32_bf16 v[64:67], v[156:159], v[214:217], v[64:67]
	s_setprio 0
	s_barrier
; #define PG8_STAGE(bufoff, gbase, voff) do { _Pragma("unroll") for (int _i = 0; _i < 2; ++_i) \
;         __builtin_amdgcn_global_load_lds((const unsigned*)((const char*)(gbase) + (voff)[_i]), (PG8_LAS unsigned*)(lds + (bufoff) + ldsw + _i * 8192), 16, 0, 0); } while (0)
; #define PG8_LDA(dst, b, h) do { _Pragma("unroll") for (int m = 0; m < 4; ++m) _Pragma("unroll") for (int k = 0; k < 2; ++k) dst[m][k] = *(const PG8_LAS bf16x8*)(lds + PG8_SA(b, h) + aoff + m * 2048 + k * 1024); } while (0)
; #define PG8_MMA(ai, bj, At, Bt) do { __builtin_amdgcn_s_setprio(1); _Pragma("unroll") for (int m = 0; m < 4; ++m) _Pragma("unroll") for (int n = 0; n < 2; ++n) _Pragma("unroll") for (int k = 0; k < 2; ++k) \
;         acc[ai][bj][m][n] = __builtin_amdgcn_mfma_f32_16x16x32_bf16(Bt[n][k], At[m][k], acc[ai][bj][m][n], 0, 0, 0); __builtin_amdgcn_s_setprio(0); } while (0)
; #define PG8_WAIT_V(n) asm volatile("s_waitcnt vmcnt(" #n ")" ::: "memory")
; #define PG8_WAIT_L(n) asm volatile("s_waitcnt lgkmcnt(" #n ")" ::: "memory")
; #define PG8_BAR __builtin_amdgcn_s_barrier()
; #define PG8_SCHED __builtin_amdgcn_sched_barrier(0)
; template <class Epi, class Sched, bool ALIGN_EPI = false, bool SP2 = false>
; __device__ __forceinline__ void gemm_phase(PG8_LAS unsigned char* lds, const Gemm g, const Sched& S, const Epi& E) {
;     ...
;         for (int t = 0; t < nt; t += 2) {
;             const bool last = (t == nt - 2);
;             const char* a1 = cA + (size_t)(t + 1) * kstepA;
;             const char* a2 = last ? nA : cA + (size_t)(t + 2) * kstepA; const char* b2 = last ? nB : cB + (size_t)(t + 2) * kstep;
;             const char* a3 = a2 + kstepA; const char* b3 = b2 + kstep;
;     ...
;             PG8_LDA(At, 1, 1); PG8_STAGE(PG8_SB(1, 0), b3, voffB); PG8_STAGE(PG8_SB(1, 1), b3 + hstep, voffB); PG8_STAGE(PG8_SA(1, 0), a3, voffA);
;             PG8_WAIT_V(8); PG8_WAIT_L(0); PG8_BAR; PG8_MMA(1, 0, At, B0); PG8_MMA(1, 1, At, B1); PG8_BAR; PG8_SCHED;
	s_add_i32 s52, s64, s2
	v_lshl_add_u64 v[178:179], v[178:179], 0, s[30:31]
	s_mov_b32 m0, s52
	ds_read_b128 v[160:163], v237 offset:49152
	ds_read_b128 v[164:167], v237 offset:50176
	ds_read_b128 v[170:173], v237 offset:51200
	ds_read_b128 v[198:201], v237 offset:52224
	ds_read_b128 v[202:205], v237 offset:53248
	ds_read_b128 v[206:209], v237 offset:54272
	ds_read_b128 v[210:213], v237 offset:55296
	ds_read_b128 v[214:217], v237 offset:56320
	global_load_lds_dwordx4 v[178:179], off
	s_add_i32 m0, s52, 0x2000
	s_add_u32 s50, s50, 0xb0080
	v_lshl_add_u64 v[178:179], v[218:219], 0, s[30:31]
	s_addc_u32 s51, s51, 0
	s_add_i32 s52, s65, s2
	global_load_lds_dwordx4 v[178:179], off
	v_lshl_add_u64 v[178:179], s[50:51], 0, v[168:169]
	s_mov_b32 m0, s52
	s_nop 0
	global_load_lds_dwordx4 v[178:179], off
	v_lshl_add_u64 v[178:179], s[50:51], 0, v[188:189]
	s_add_i32 m0, s52, 0x2000
	s_nop 0
	global_load_lds_dwordx4 v[178:179], off
	v_lshl_add_u64 v[178:179], s[48:49], 0, v[192:193]
	s_mov_b32 m0, s57
	s_nop 0
	global_load_lds_dwordx4 v[178:179], off
	v_lshl_add_u64 v[178:179], s[48:49], 0, v[190:191]
	s_mov_b32 m0, s60
	s_nop 0
	global_load_lds_dwordx4 v[178:179], off
	s_waitcnt vmcnt(8)
	s_waitcnt lgkmcnt(0)
	s_barrier
	s_setprio 1
	s_waitcnt lgkmcnt(0)
	v_mfma_f32_16x16x32_bf16 v[60:63], v[128:131], v[160:163], v[60:63]
	v_mfma_f32_16x16x32_bf16 v[56:59], v[136:139], v[160:163], v[56:59]
	v_mfma_f32_16x16x32_bf16 v[44:47], v[128:131], v[170:173], v[44:47]
	v_mfma_f32_16x16x32_bf16 v[40:43], v[136:139], v[170:173], v[40:43]
	v_mfma_f32_16x16x32_bf16 v[28:31], v[128:131], v[202:205], v[28:31]
	v_mfma_f32_16x16x32_bf16 v[24:27], v[136:139], v[202:205], v[24:27]
	v_mfma_f32_16x16x32_bf16 v[12:15], v[128:131], v[210:213], v[12:15]
	v_mfma_f32_16x16x32_bf16 v[8:11], v[136:139], v[210:213], v[8:11]
	v_mfma_f32_16x16x32_bf16 v[60:63], v[132:135], v[164:167], v[60:63]
	v_mfma_f32_16x16x32_bf16 v[56:59], v[140:143], v[164:167], v[56:59]
	v_mfma_f32_16x16x32_bf16 v[44:47], v[132:135], v[198:201], v[44:47]
	v_mfma_f32_16x16x32_bf16 v[40:43], v[140:143], v[198:201], v[40:43]
	v_mfma_f32_16x16x32_bf16 v[28:31], v[132:135], v[206:209], v[28:31]
	v_mfma_f32_16x16x32_bf16 v[24:27], v[140:143], v[206:209], v[24:27]
	v_mfma_f32_16x16x32_bf16 v[12:15], v[132:135], v[214:217], v[12:15]
	v_mfma_f32_16x16x32_bf16 v[8:11], v[140:143], v[214:217], v[8:11]
	s_setprio 0
	s_setprio 1
	v_mfma_f32_16x16x32_bf16 v[52:55], v[144:147], v[160:163], v[52:55]
	v_mfma_f32_16x16x32_bf16 v[48:51], v[152:155], v[160:163], v[48:51]
	v_mfma_f32_16x16x32_bf16 v[36:39], v[144:147], v[170:173], v[36:39]
	v_mfma_f32_16x16x32_bf16 v[32:35], v[152:155], v[170:173], v[32:35]
	v_mfma_f32_16x16x32_bf16 v[20:23], v[144:147], v[202:205], v[20:23]
	v_mfma_f32_16x16x32_bf16 v[16:19], v[152:155], v[202:205], v[16:19]
	v_mfma_f32_16x16x32_bf16 v[4:7], v[144:147], v[210:213], v[4:7]
	v_mfma_f32_16x16x32_bf16 v[0:3], v[152:155], v[210:213], v[0:3]
	v_mfma_f32_16x16x32_bf16 v[52:55], v[148:151], v[164:167], v[52:55]
	v_mfma_f32_16x16x32_bf16 v[48:51], v[156:159], v[164:167], v[48:51]
	v_mfma_f32_16x16x32_bf16 v[36:39], v[148:151], v[198:201], v[36:39]
	v_mfma_f32_16x16x32_bf16 v[32:35], v[156:159], v[198:201], v[32:35]
	v_mfma_f32_16x16x32_bf16 v[20:23], v[148:151], v[206:209], v[20:23]
	v_mfma_f32_16x16x32_bf16 v[16:19], v[156:159], v[206:209], v[16:19]
	v_mfma_f32_16x16x32_bf16 v[4:7], v[148:151], v[214:217], v[4:7]
	v_mfma_f32_16x16x32_bf16 v[0:3], v[156:159], v[214:217], v[0:3]
	s_setprio 0
	s_barrier
	s_add_i32 s7, s7, 2
	s_add_u32 s5, s5, 0x100
	s_addc_u32 s6, s6, 0
	s_add_u32 s38, s38, 0x8000
	s_addc_u32 s39, s39, 0
